# v11 plus gaxpy: the 16 per-expert coefficient ds_bpermutes of each token issued back to back into own registers with counted lgkmcnt waits
# speedup vs baseline: 1.0222x; 1.0110x over previous
.LBB0_662:
	s_or_b64 exec, exec, s[0:1]
	v_add_u32_e32 v142, s24, v140
	v_min_i32_e32 v160, 0x3fff, v142
	v_ashrrev_i32_e32 v161, 31, v160
	v_lshlrev_b64 v[160:161], 9, v[160:161]
	v_lshl_or_b32 v160, v128, 2, v160
	v_lshl_add_u64 v[162:163], s[14:15], 0, v[160:161]
	v_or_b32_e32 v164, 0x100, v160
	v_mov_b32_e32 v165, v161
	v_lshl_add_u64 v[160:161], s[16:17], 0, v[160:161]
	v_lshl_add_u64 v[166:167], s[14:15], 0, v[164:165]
	v_lshl_add_u64 v[164:165], s[16:17], 0, v[164:165]
	global_load_dword v158, v[162:163], off
	global_load_dword v157, v[166:167], off
	global_load_dword v153, v[160:161], off
	global_load_dword v154, v[164:165], off
	s_waitcnt vmcnt(21)
	ds_bpermute_b32 v160, v133, v159
	ds_bpermute_b32 v192, v144, v159
	ds_bpermute_b32 v194, v145, v159
	ds_bpermute_b32 v196, v146, v159
	ds_bpermute_b32 v198, v147, v159
	ds_bpermute_b32 v200, v148, v159
	ds_bpermute_b32 v202, v149, v159
	ds_bpermute_b32 v204, v150, v159
	ds_bpermute_b32 v206, v133, v156
	ds_bpermute_b32 v208, v144, v156
	ds_bpermute_b32 v210, v145, v156
	ds_bpermute_b32 v212, v146, v156
	ds_bpermute_b32 v214, v147, v156
	ds_bpermute_b32 v216, v148, v156
	ds_bpermute_b32 v218, v149, v156
	ds_bpermute_b32 v220, v150, v156
	s_waitcnt vmcnt(5)
	v_cvt_pk_f32_fp8_e32 v[162:163], v4
	v_cvt_pk_f32_fp8_sdwa v[164:165], v4 src0_sel:WORD_1
	v_cvt_pk_f32_fp8_e32 v[166:167], v5
	v_cvt_pk_f32_fp8_sdwa v[168:169], v5 src0_sel:WORD_1
	v_cvt_pk_f32_fp8_e32 v[170:171], v6
	v_cvt_pk_f32_fp8_sdwa v[172:173], v6 src0_sel:WORD_1
	v_cvt_pk_f32_fp8_e32 v[174:175], v7
	v_cvt_pk_f32_fp8_sdwa v[176:177], v7 src0_sel:WORD_1
	s_waitcnt lgkmcnt(15)
	v_pk_fma_f32 v[162:163], v[162:163], v[160:161], 0 op_sel_hi:[1,0,0]
	v_pk_fma_f32 v[164:165], v[164:165], v[160:161], 0 op_sel_hi:[1,0,0]
	v_pk_fma_f32 v[166:167], v[166:167], v[160:161], 0 op_sel_hi:[1,0,0]
	v_pk_fma_f32 v[168:169], v[168:169], v[160:161], 0 op_sel_hi:[1,0,0]
	v_pk_fma_f32 v[170:171], v[170:171], v[160:161], 0 op_sel_hi:[1,0,0]
	v_pk_fma_f32 v[172:173], v[172:173], v[160:161], 0 op_sel_hi:[1,0,0]
	v_pk_fma_f32 v[174:175], v[174:175], v[160:161], 0 op_sel_hi:[1,0,0]
	v_pk_fma_f32 v[160:161], v[176:177], v[160:161], 0 op_sel_hi:[1,0,0]
	v_cvt_pk_f32_fp8_e32 v[180:181], v0
	v_cvt_pk_f32_fp8_sdwa v[186:187], v0 src0_sel:WORD_1
	v_cvt_pk_f32_fp8_e32 v[188:189], v1
	v_cvt_pk_f32_fp8_sdwa v[190:191], v1 src0_sel:WORD_1
	s_waitcnt lgkmcnt(14)
	v_pk_fma_f32 v[162:163], v[180:181], v[192:193], v[162:163] op_sel_hi:[1,0,1]
	v_pk_fma_f32 v[164:165], v[186:187], v[192:193], v[164:165] op_sel_hi:[1,0,1]
	v_pk_fma_f32 v[166:167], v[188:189], v[192:193], v[166:167] op_sel_hi:[1,0,1]
	v_pk_fma_f32 v[168:169], v[190:191], v[192:193], v[168:169] op_sel_hi:[1,0,1]
	v_cvt_pk_f32_fp8_e32 v[180:181], v2
	v_cvt_pk_f32_fp8_sdwa v[186:187], v2 src0_sel:WORD_1
	v_cvt_pk_f32_fp8_e32 v[188:189], v3
	v_cvt_pk_f32_fp8_sdwa v[190:191], v3 src0_sel:WORD_1
	v_pk_fma_f32 v[170:171], v[180:181], v[192:193], v[170:171] op_sel_hi:[1,0,1]
	v_pk_fma_f32 v[172:173], v[186:187], v[192:193], v[172:173] op_sel_hi:[1,0,1]
	v_pk_fma_f32 v[174:175], v[188:189], v[192:193], v[174:175] op_sel_hi:[1,0,1]
	v_pk_fma_f32 v[160:161], v[190:191], v[192:193], v[160:161] op_sel_hi:[1,0,1]
	v_cvt_pk_f32_fp8_e32 v[180:181], v12
	v_cvt_pk_f32_fp8_sdwa v[186:187], v12 src0_sel:WORD_1
	v_cvt_pk_f32_fp8_e32 v[188:189], v13
	v_cvt_pk_f32_fp8_sdwa v[190:191], v13 src0_sel:WORD_1
	s_waitcnt lgkmcnt(13)
	v_pk_fma_f32 v[162:163], v[180:181], v[194:195], v[162:163] op_sel_hi:[1,0,1]
	v_pk_fma_f32 v[164:165], v[186:187], v[194:195], v[164:165] op_sel_hi:[1,0,1]
	v_pk_fma_f32 v[166:167], v[188:189], v[194:195], v[166:167] op_sel_hi:[1,0,1]
	v_pk_fma_f32 v[168:169], v[190:191], v[194:195], v[168:169] op_sel_hi:[1,0,1]
	v_cvt_pk_f32_fp8_e32 v[180:181], v14
	v_cvt_pk_f32_fp8_sdwa v[186:187], v14 src0_sel:WORD_1
	v_cvt_pk_f32_fp8_e32 v[188:189], v15
	v_cvt_pk_f32_fp8_sdwa v[190:191], v15 src0_sel:WORD_1
	v_pk_fma_f32 v[170:171], v[180:181], v[194:195], v[170:171] op_sel_hi:[1,0,1]
	v_pk_fma_f32 v[172:173], v[186:187], v[194:195], v[172:173] op_sel_hi:[1,0,1]
	v_pk_fma_f32 v[174:175], v[188:189], v[194:195], v[174:175] op_sel_hi:[1,0,1]
	v_pk_fma_f32 v[160:161], v[190:191], v[194:195], v[160:161] op_sel_hi:[1,0,1]
	v_cvt_pk_f32_fp8_e32 v[180:181], v8
	v_cvt_pk_f32_fp8_sdwa v[186:187], v8 src0_sel:WORD_1
	v_cvt_pk_f32_fp8_e32 v[188:189], v9
	v_cvt_pk_f32_fp8_sdwa v[190:191], v9 src0_sel:WORD_1
	s_waitcnt lgkmcnt(12)
	v_pk_fma_f32 v[162:163], v[180:181], v[196:197], v[162:163] op_sel_hi:[1,0,1]
	v_pk_fma_f32 v[164:165], v[186:187], v[196:197], v[164:165] op_sel_hi:[1,0,1]
	v_pk_fma_f32 v[166:167], v[188:189], v[196:197], v[166:167] op_sel_hi:[1,0,1]
	v_pk_fma_f32 v[168:169], v[190:191], v[196:197], v[168:169] op_sel_hi:[1,0,1]
	v_cvt_pk_f32_fp8_e32 v[180:181], v10
	v_cvt_pk_f32_fp8_sdwa v[186:187], v10 src0_sel:WORD_1
	v_cvt_pk_f32_fp8_e32 v[188:189], v11
	v_cvt_pk_f32_fp8_sdwa v[190:191], v11 src0_sel:WORD_1
	v_pk_fma_f32 v[170:171], v[180:181], v[196:197], v[170:171] op_sel_hi:[1,0,1]
	v_pk_fma_f32 v[172:173], v[186:187], v[196:197], v[172:173] op_sel_hi:[1,0,1]
	v_pk_fma_f32 v[174:175], v[188:189], v[196:197], v[174:175] op_sel_hi:[1,0,1]
	v_pk_fma_f32 v[160:161], v[190:191], v[196:197], v[160:161] op_sel_hi:[1,0,1]
	v_cvt_pk_f32_fp8_e32 v[180:181], v20
	v_cvt_pk_f32_fp8_sdwa v[186:187], v20 src0_sel:WORD_1
	v_cvt_pk_f32_fp8_e32 v[188:189], v21
	v_cvt_pk_f32_fp8_sdwa v[190:191], v21 src0_sel:WORD_1
	s_waitcnt lgkmcnt(11)
	v_pk_fma_f32 v[162:163], v[180:181], v[198:199], v[162:163] op_sel_hi:[1,0,1]
	v_pk_fma_f32 v[164:165], v[186:187], v[198:199], v[164:165] op_sel_hi:[1,0,1]
	v_pk_fma_f32 v[166:167], v[188:189], v[198:199], v[166:167] op_sel_hi:[1,0,1]
	v_pk_fma_f32 v[168:169], v[190:191], v[198:199], v[168:169] op_sel_hi:[1,0,1]
	v_cvt_pk_f32_fp8_e32 v[180:181], v22
	v_cvt_pk_f32_fp8_sdwa v[186:187], v22 src0_sel:WORD_1
	v_cvt_pk_f32_fp8_e32 v[188:189], v23
	v_cvt_pk_f32_fp8_sdwa v[190:191], v23 src0_sel:WORD_1
	v_pk_fma_f32 v[170:171], v[180:181], v[198:199], v[170:171] op_sel_hi:[1,0,1]
	v_pk_fma_f32 v[172:173], v[186:187], v[198:199], v[172:173] op_sel_hi:[1,0,1]
	v_pk_fma_f32 v[174:175], v[188:189], v[198:199], v[174:175] op_sel_hi:[1,0,1]
	v_pk_fma_f32 v[160:161], v[190:191], v[198:199], v[160:161] op_sel_hi:[1,0,1]
	v_cvt_pk_f32_fp8_e32 v[180:181], v16
	v_cvt_pk_f32_fp8_sdwa v[186:187], v16 src0_sel:WORD_1
	v_cvt_pk_f32_fp8_e32 v[188:189], v17
	v_cvt_pk_f32_fp8_sdwa v[190:191], v17 src0_sel:WORD_1
	s_waitcnt lgkmcnt(10)
	v_pk_fma_f32 v[162:163], v[180:181], v[200:201], v[162:163] op_sel_hi:[1,0,1]
	v_pk_fma_f32 v[164:165], v[186:187], v[200:201], v[164:165] op_sel_hi:[1,0,1]
	v_pk_fma_f32 v[166:167], v[188:189], v[200:201], v[166:167] op_sel_hi:[1,0,1]
	v_pk_fma_f32 v[168:169], v[190:191], v[200:201], v[168:169] op_sel_hi:[1,0,1]
	v_cvt_pk_f32_fp8_e32 v[180:181], v18
	v_cvt_pk_f32_fp8_sdwa v[186:187], v18 src0_sel:WORD_1
	v_cvt_pk_f32_fp8_e32 v[188:189], v19
	v_cvt_pk_f32_fp8_sdwa v[190:191], v19 src0_sel:WORD_1
	v_pk_fma_f32 v[170:171], v[180:181], v[200:201], v[170:171] op_sel_hi:[1,0,1]
	v_pk_fma_f32 v[172:173], v[186:187], v[200:201], v[172:173] op_sel_hi:[1,0,1]
	v_pk_fma_f32 v[174:175], v[188:189], v[200:201], v[174:175] op_sel_hi:[1,0,1]
	v_pk_fma_f32 v[160:161], v[190:191], v[200:201], v[160:161] op_sel_hi:[1,0,1]
	v_cvt_pk_f32_fp8_e32 v[180:181], v28
	v_cvt_pk_f32_fp8_sdwa v[186:187], v28 src0_sel:WORD_1
	v_cvt_pk_f32_fp8_e32 v[188:189], v29
	v_cvt_pk_f32_fp8_sdwa v[190:191], v29 src0_sel:WORD_1
	s_waitcnt lgkmcnt(9)
	v_pk_fma_f32 v[162:163], v[180:181], v[202:203], v[162:163] op_sel_hi:[1,0,1]
	v_pk_fma_f32 v[164:165], v[186:187], v[202:203], v[164:165] op_sel_hi:[1,0,1]
	v_pk_fma_f32 v[166:167], v[188:189], v[202:203], v[166:167] op_sel_hi:[1,0,1]
	v_pk_fma_f32 v[168:169], v[190:191], v[202:203], v[168:169] op_sel_hi:[1,0,1]
	v_cvt_pk_f32_fp8_e32 v[180:181], v30
	v_cvt_pk_f32_fp8_sdwa v[186:187], v30 src0_sel:WORD_1
	v_cvt_pk_f32_fp8_e32 v[188:189], v31
	v_cvt_pk_f32_fp8_sdwa v[190:191], v31 src0_sel:WORD_1
	v_pk_fma_f32 v[170:171], v[180:181], v[202:203], v[170:171] op_sel_hi:[1,0,1]
	v_pk_fma_f32 v[172:173], v[186:187], v[202:203], v[172:173] op_sel_hi:[1,0,1]
	v_pk_fma_f32 v[174:175], v[188:189], v[202:203], v[174:175] op_sel_hi:[1,0,1]
	v_pk_fma_f32 v[160:161], v[190:191], v[202:203], v[160:161] op_sel_hi:[1,0,1]
	v_cvt_pk_f32_fp8_e32 v[180:181], v24
	v_cvt_pk_f32_fp8_sdwa v[186:187], v24 src0_sel:WORD_1
	v_cvt_pk_f32_fp8_e32 v[188:189], v25
	v_cvt_pk_f32_fp8_sdwa v[190:191], v25 src0_sel:WORD_1
	s_waitcnt lgkmcnt(8)
	v_pk_fma_f32 v[162:163], v[180:181], v[204:205], v[162:163] op_sel_hi:[1,0,1]
	v_pk_fma_f32 v[164:165], v[186:187], v[204:205], v[164:165] op_sel_hi:[1,0,1]
	v_pk_fma_f32 v[166:167], v[188:189], v[204:205], v[166:167] op_sel_hi:[1,0,1]
	v_pk_fma_f32 v[168:169], v[190:191], v[204:205], v[168:169] op_sel_hi:[1,0,1]
	v_cvt_pk_f32_fp8_e32 v[180:181], v26
	v_cvt_pk_f32_fp8_sdwa v[186:187], v26 src0_sel:WORD_1
	v_cvt_pk_f32_fp8_e32 v[188:189], v27
	v_cvt_pk_f32_fp8_sdwa v[190:191], v27 src0_sel:WORD_1
	v_pk_fma_f32 v[170:171], v[180:181], v[204:205], v[170:171] op_sel_hi:[1,0,1]
	v_pk_fma_f32 v[172:173], v[186:187], v[204:205], v[172:173] op_sel_hi:[1,0,1]
	v_pk_fma_f32 v[174:175], v[188:189], v[204:205], v[174:175] op_sel_hi:[1,0,1]
	v_pk_fma_f32 v[160:161], v[190:191], v[204:205], v[160:161] op_sel_hi:[1,0,1]
	v_cvt_pk_f32_fp8_e32 v[180:181], v36
	v_cvt_pk_f32_fp8_sdwa v[186:187], v36 src0_sel:WORD_1
	v_cvt_pk_f32_fp8_e32 v[188:189], v37
	v_cvt_pk_f32_fp8_sdwa v[190:191], v37 src0_sel:WORD_1
	s_waitcnt lgkmcnt(7)
	v_pk_fma_f32 v[162:163], v[180:181], v[206:207], v[162:163] op_sel_hi:[1,0,1]
	v_pk_fma_f32 v[164:165], v[186:187], v[206:207], v[164:165] op_sel_hi:[1,0,1]
	v_pk_fma_f32 v[166:167], v[188:189], v[206:207], v[166:167] op_sel_hi:[1,0,1]
	v_pk_fma_f32 v[168:169], v[190:191], v[206:207], v[168:169] op_sel_hi:[1,0,1]
	v_cvt_pk_f32_fp8_e32 v[180:181], v38
	v_cvt_pk_f32_fp8_sdwa v[186:187], v38 src0_sel:WORD_1
	v_cvt_pk_f32_fp8_e32 v[188:189], v39
	v_cvt_pk_f32_fp8_sdwa v[190:191], v39 src0_sel:WORD_1
	v_pk_fma_f32 v[170:171], v[180:181], v[206:207], v[170:171] op_sel_hi:[1,0,1]
	v_pk_fma_f32 v[172:173], v[186:187], v[206:207], v[172:173] op_sel_hi:[1,0,1]
	v_pk_fma_f32 v[174:175], v[188:189], v[206:207], v[174:175] op_sel_hi:[1,0,1]
	v_pk_fma_f32 v[160:161], v[190:191], v[206:207], v[160:161] op_sel_hi:[1,0,1]
	v_cvt_pk_f32_fp8_e32 v[180:181], v32
	v_cvt_pk_f32_fp8_sdwa v[186:187], v32 src0_sel:WORD_1
	v_cvt_pk_f32_fp8_e32 v[188:189], v33
	v_cvt_pk_f32_fp8_sdwa v[190:191], v33 src0_sel:WORD_1
	s_waitcnt lgkmcnt(6)
	v_pk_fma_f32 v[162:163], v[180:181], v[208:209], v[162:163] op_sel_hi:[1,0,1]
	v_pk_fma_f32 v[164:165], v[186:187], v[208:209], v[164:165] op_sel_hi:[1,0,1]
	v_pk_fma_f32 v[166:167], v[188:189], v[208:209], v[166:167] op_sel_hi:[1,0,1]
	v_pk_fma_f32 v[168:169], v[190:191], v[208:209], v[168:169] op_sel_hi:[1,0,1]
	v_cvt_pk_f32_fp8_e32 v[180:181], v34
	v_cvt_pk_f32_fp8_sdwa v[186:187], v34 src0_sel:WORD_1
	v_cvt_pk_f32_fp8_e32 v[188:189], v35
	v_cvt_pk_f32_fp8_sdwa v[190:191], v35 src0_sel:WORD_1
	v_pk_fma_f32 v[170:171], v[180:181], v[208:209], v[170:171] op_sel_hi:[1,0,1]
	v_pk_fma_f32 v[172:173], v[186:187], v[208:209], v[172:173] op_sel_hi:[1,0,1]
	v_pk_fma_f32 v[174:175], v[188:189], v[208:209], v[174:175] op_sel_hi:[1,0,1]
	v_pk_fma_f32 v[160:161], v[190:191], v[208:209], v[160:161] op_sel_hi:[1,0,1]
	v_cvt_pk_f32_fp8_e32 v[180:181], v52
	v_cvt_pk_f32_fp8_sdwa v[186:187], v52 src0_sel:WORD_1
	v_cvt_pk_f32_fp8_e32 v[188:189], v53
	v_cvt_pk_f32_fp8_sdwa v[190:191], v53 src0_sel:WORD_1
	s_waitcnt lgkmcnt(5)
	v_pk_fma_f32 v[162:163], v[180:181], v[210:211], v[162:163] op_sel_hi:[1,0,1]
	v_pk_fma_f32 v[164:165], v[186:187], v[210:211], v[164:165] op_sel_hi:[1,0,1]
	v_pk_fma_f32 v[166:167], v[188:189], v[210:211], v[166:167] op_sel_hi:[1,0,1]
	v_pk_fma_f32 v[168:169], v[190:191], v[210:211], v[168:169] op_sel_hi:[1,0,1]
	v_cvt_pk_f32_fp8_e32 v[180:181], v54
	v_cvt_pk_f32_fp8_sdwa v[186:187], v54 src0_sel:WORD_1
	v_cvt_pk_f32_fp8_e32 v[188:189], v55
	v_cvt_pk_f32_fp8_sdwa v[190:191], v55 src0_sel:WORD_1
	v_pk_fma_f32 v[170:171], v[180:181], v[210:211], v[170:171] op_sel_hi:[1,0,1]
	v_pk_fma_f32 v[172:173], v[186:187], v[210:211], v[172:173] op_sel_hi:[1,0,1]
	v_pk_fma_f32 v[174:175], v[188:189], v[210:211], v[174:175] op_sel_hi:[1,0,1]
	v_pk_fma_f32 v[160:161], v[190:191], v[210:211], v[160:161] op_sel_hi:[1,0,1]
	v_cvt_pk_f32_fp8_e32 v[180:181], v48
	v_cvt_pk_f32_fp8_sdwa v[186:187], v48 src0_sel:WORD_1
	v_cvt_pk_f32_fp8_e32 v[188:189], v49
	v_cvt_pk_f32_fp8_sdwa v[190:191], v49 src0_sel:WORD_1
	s_waitcnt lgkmcnt(4)
	v_pk_fma_f32 v[162:163], v[180:181], v[212:213], v[162:163] op_sel_hi:[1,0,1]
	v_pk_fma_f32 v[164:165], v[186:187], v[212:213], v[164:165] op_sel_hi:[1,0,1]
	v_pk_fma_f32 v[166:167], v[188:189], v[212:213], v[166:167] op_sel_hi:[1,0,1]
	v_pk_fma_f32 v[168:169], v[190:191], v[212:213], v[168:169] op_sel_hi:[1,0,1]
	v_cvt_pk_f32_fp8_e32 v[180:181], v50
	v_cvt_pk_f32_fp8_sdwa v[186:187], v50 src0_sel:WORD_1
	v_cvt_pk_f32_fp8_e32 v[188:189], v51
	v_cvt_pk_f32_fp8_sdwa v[190:191], v51 src0_sel:WORD_1
	v_pk_fma_f32 v[170:171], v[180:181], v[212:213], v[170:171] op_sel_hi:[1,0,1]
	v_pk_fma_f32 v[172:173], v[186:187], v[212:213], v[172:173] op_sel_hi:[1,0,1]
	v_pk_fma_f32 v[174:175], v[188:189], v[212:213], v[174:175] op_sel_hi:[1,0,1]
	v_pk_fma_f32 v[160:161], v[190:191], v[212:213], v[160:161] op_sel_hi:[1,0,1]
	v_cvt_pk_f32_fp8_e32 v[180:181], v60
	v_cvt_pk_f32_fp8_sdwa v[186:187], v60 src0_sel:WORD_1
	v_cvt_pk_f32_fp8_e32 v[188:189], v61
	v_cvt_pk_f32_fp8_sdwa v[190:191], v61 src0_sel:WORD_1
	s_waitcnt lgkmcnt(3)
	v_pk_fma_f32 v[162:163], v[180:181], v[214:215], v[162:163] op_sel_hi:[1,0,1]
	v_pk_fma_f32 v[164:165], v[186:187], v[214:215], v[164:165] op_sel_hi:[1,0,1]
	v_pk_fma_f32 v[166:167], v[188:189], v[214:215], v[166:167] op_sel_hi:[1,0,1]
	v_pk_fma_f32 v[168:169], v[190:191], v[214:215], v[168:169] op_sel_hi:[1,0,1]
	v_cvt_pk_f32_fp8_e32 v[180:181], v62
	v_cvt_pk_f32_fp8_sdwa v[186:187], v62 src0_sel:WORD_1
	v_cvt_pk_f32_fp8_e32 v[188:189], v63
	v_cvt_pk_f32_fp8_sdwa v[190:191], v63 src0_sel:WORD_1
	v_pk_fma_f32 v[170:171], v[180:181], v[214:215], v[170:171] op_sel_hi:[1,0,1]
	v_pk_fma_f32 v[172:173], v[186:187], v[214:215], v[172:173] op_sel_hi:[1,0,1]
	v_pk_fma_f32 v[174:175], v[188:189], v[214:215], v[174:175] op_sel_hi:[1,0,1]
	v_pk_fma_f32 v[160:161], v[190:191], v[214:215], v[160:161] op_sel_hi:[1,0,1]
	v_cvt_pk_f32_fp8_e32 v[180:181], v56
	v_cvt_pk_f32_fp8_sdwa v[186:187], v56 src0_sel:WORD_1
	v_cvt_pk_f32_fp8_e32 v[188:189], v57
	v_cvt_pk_f32_fp8_sdwa v[190:191], v57 src0_sel:WORD_1
	s_waitcnt lgkmcnt(2)
	v_pk_fma_f32 v[162:163], v[180:181], v[216:217], v[162:163] op_sel_hi:[1,0,1]
	v_pk_fma_f32 v[164:165], v[186:187], v[216:217], v[164:165] op_sel_hi:[1,0,1]
	v_pk_fma_f32 v[166:167], v[188:189], v[216:217], v[166:167] op_sel_hi:[1,0,1]
	v_pk_fma_f32 v[168:169], v[190:191], v[216:217], v[168:169] op_sel_hi:[1,0,1]
	v_cvt_pk_f32_fp8_e32 v[180:181], v58
	v_cvt_pk_f32_fp8_sdwa v[186:187], v58 src0_sel:WORD_1
	v_cvt_pk_f32_fp8_e32 v[188:189], v59
	v_cvt_pk_f32_fp8_sdwa v[190:191], v59 src0_sel:WORD_1
	v_pk_fma_f32 v[170:171], v[180:181], v[216:217], v[170:171] op_sel_hi:[1,0,1]
	v_pk_fma_f32 v[172:173], v[186:187], v[216:217], v[172:173] op_sel_hi:[1,0,1]
	v_pk_fma_f32 v[174:175], v[188:189], v[216:217], v[174:175] op_sel_hi:[1,0,1]
	v_pk_fma_f32 v[160:161], v[190:191], v[216:217], v[160:161] op_sel_hi:[1,0,1]
	v_cvt_pk_f32_fp8_e32 v[180:181], v72
	v_cvt_pk_f32_fp8_sdwa v[186:187], v72 src0_sel:WORD_1
	v_cvt_pk_f32_fp8_e32 v[188:189], v73
	v_cvt_pk_f32_fp8_sdwa v[190:191], v73 src0_sel:WORD_1
	s_waitcnt lgkmcnt(1)
	v_pk_fma_f32 v[162:163], v[180:181], v[218:219], v[162:163] op_sel_hi:[1,0,1]
	v_pk_fma_f32 v[164:165], v[186:187], v[218:219], v[164:165] op_sel_hi:[1,0,1]
	v_pk_fma_f32 v[166:167], v[188:189], v[218:219], v[166:167] op_sel_hi:[1,0,1]
	v_pk_fma_f32 v[168:169], v[190:191], v[218:219], v[168:169] op_sel_hi:[1,0,1]
	v_cvt_pk_f32_fp8_e32 v[180:181], v74
	v_cvt_pk_f32_fp8_sdwa v[186:187], v74 src0_sel:WORD_1
	v_cvt_pk_f32_fp8_e32 v[188:189], v75
	v_cvt_pk_f32_fp8_sdwa v[190:191], v75 src0_sel:WORD_1
	v_pk_fma_f32 v[170:171], v[180:181], v[218:219], v[170:171] op_sel_hi:[1,0,1]
	v_pk_fma_f32 v[172:173], v[186:187], v[218:219], v[172:173] op_sel_hi:[1,0,1]
	v_pk_fma_f32 v[174:175], v[188:189], v[218:219], v[174:175] op_sel_hi:[1,0,1]
	v_pk_fma_f32 v[160:161], v[190:191], v[218:219], v[160:161] op_sel_hi:[1,0,1]
	v_cvt_pk_f32_fp8_e32 v[176:177], v68
	v_cvt_pk_f32_fp8_sdwa v[180:181], v68 src0_sel:WORD_1
	v_cvt_pk_f32_fp8_e32 v[186:187], v69
	v_cvt_pk_f32_fp8_sdwa v[188:189], v69 src0_sel:WORD_1
	s_waitcnt vmcnt(2) lgkmcnt(0)
	v_pk_fma_f32 v[162:163], v[176:177], v[220:221], v[162:163] op_sel_hi:[1,0,1]
	v_pk_fma_f32 v[164:165], v[180:181], v[220:221], v[164:165] op_sel_hi:[1,0,1]
	v_pk_fma_f32 v[166:167], v[186:187], v[220:221], v[166:167] op_sel_hi:[1,0,1]
	v_pk_fma_f32 v[168:169], v[188:189], v[220:221], v[168:169] op_sel_hi:[1,0,1]
	v_cvt_pk_f32_fp8_e32 v[176:177], v70
	v_cvt_pk_f32_fp8_sdwa v[180:181], v70 src0_sel:WORD_1
	v_cvt_pk_f32_fp8_e32 v[186:187], v71
	v_cvt_pk_f32_fp8_sdwa v[188:189], v71 src0_sel:WORD_1
	v_pk_fma_f32 v[170:171], v[176:177], v[220:221], v[170:171] op_sel_hi:[1,0,1]
	v_pk_fma_f32 v[172:173], v[180:181], v[220:221], v[172:173] op_sel_hi:[1,0,1]
	v_pk_fma_f32 v[174:175], v[186:187], v[220:221], v[174:175] op_sel_hi:[1,0,1]
	v_pk_fma_f32 v[160:161], v[188:189], v[220:221], v[160:161] op_sel_hi:[1,0,1]
	v_permlane32_swap_b32_e32 v162, v170
	v_permlane32_swap_b32_e32 v163, v171
	v_permlane32_swap_b32_e32 v164, v172
	v_permlane32_swap_b32_e32 v165, v173
	v_permlane32_swap_b32_e32 v166, v174
	v_permlane32_swap_b32_e32 v167, v175
	v_permlane32_swap_b32_e32 v168, v160
	v_permlane32_swap_b32_e32 v169, v161
	v_add_f32_e32 v162, v162, v170
	v_add_f32_e32 v163, v163, v171
	v_add_f32_e32 v164, v164, v172
	v_add_f32_e32 v165, v165, v173
	v_add_f32_e32 v166, v166, v174
	v_add_f32_e32 v167, v167, v175
	v_add_f32_e32 v160, v168, v160
	v_add_f32_e32 v161, v169, v161
	v_permlane16_swap_b32_e32 v162, v166
	v_permlane16_swap_b32_e32 v163, v167
	v_permlane16_swap_b32_e32 v164, v160
	v_permlane16_swap_b32_e32 v165, v161
	v_pk_add_f32 v[162:163], v[162:163], v[166:167]
	v_pk_add_f32 v[160:161], v[164:165], v[160:161]
	v_ashrrev_i32_e32 v141, 31, v140
	v_cndmask_b32_e32 v156, v162, v160, vcc
	v_lshlrev_b64 v[168:169], 10, v[140:141]
	v_cndmask_b32_e32 v167, v161, v163, vcc
	v_mov_b32_dpp v164, v156 row_ror:8 row_mask:0xf bank_mask:0xf bound_ctrl:1
	v_cndmask_b32_e32 v156, v163, v161, vcc
	v_cndmask_b32_e32 v166, v160, v162, vcc
	v_or_b32_e32 v168, v168, v132
	v_mov_b32_dpp v165, v156 row_ror:8 row_mask:0xf bank_mask:0xf bound_ctrl:1
	v_pk_add_f32 v[160:161], v[166:167], v[164:165]
	v_lshl_add_u64 v[170:171], v[168:169], 2, s[70:71]
	v_pk_add_f32 v[160:161], v[134:135], v[160:161]
	global_store_dwordx2 v[170:171], v[160:161], off
	v_cvt_pk_bf16_f32 v156, v160, v161
	v_lshl_add_u64 v[162:163], v[168:169], 1, s[12:13]
	v_pk_mul_f32 v[160:161], v[160:161], v[160:161]
	global_store_dword v[162:163], v156, off
	v_add_f32_e32 v156, v160, v161
	s_nop 1
	v_add_f32_dpp v156, v156, v156 quad_perm:[1,0,3,2] row_mask:0xf bank_mask:0xf bound_ctrl:1
	s_nop 1
	v_add_f32_dpp v156, v156, v156 quad_perm:[2,3,0,1] row_mask:0xf bank_mask:0xf bound_ctrl:1
	s_nop 1
	v_add_f32_dpp v156, v156, v156 row_ror:4 row_mask:0xf bank_mask:0xf bound_ctrl:1
	s_nop 1
	v_add_f32_dpp v156, v156, v156 row_ror:8 row_mask:0xf bank_mask:0xf bound_ctrl:1
	v_mov_b32_e32 v159, v156
	s_nop 1
	v_permlane16_swap_b32_e32 v156, v159
	v_add_f32_e32 v156, v156, v159
	v_mov_b32_e32 v159, v156
	s_nop 1
	v_permlane32_swap_b32_e32 v156, v159
	s_and_saveexec_b64 s[0:1], s[4:5]
	s_cbranch_execz .LBB0_664
	v_lshlrev_b64 v[160:161], 5, v[140:141]
	v_add_f32_e32 v156, v156, v159
	v_lshl_add_u64 v[160:161], s[18:19], 0, v[160:161]
	global_store_dword v[160:161], v156, off

.LBB0_667:
	s_or_b64 exec, exec, s[6:7]
	v_add_u32_e32 v140, s25, v140
	v_min_i32_e32 v140, 0x3fff, v140
	v_ashrrev_i32_e32 v141, 31, v140
	v_lshlrev_b64 v[140:141], 9, v[140:141]
	v_lshl_or_b32 v140, v128, 2, v140
	v_lshl_add_u64 v[142:143], s[14:15], 0, v[140:141]
	v_or_b32_e32 v156, 0x100, v140
	v_mov_b32_e32 v157, v141
	v_lshl_add_u64 v[140:141], s[16:17], 0, v[140:141]
	v_lshl_add_u64 v[158:159], s[14:15], 0, v[156:157]
	v_lshl_add_u64 v[156:157], s[16:17], 0, v[156:157]
	global_load_dword v143, v[142:143], off
	s_nop 0
	global_load_dword v152, v[158:159], off
	s_nop 0
	global_load_dword v141, v[140:141], off
	s_nop 0
	global_load_dword v140, v[156:157], off
	ds_bpermute_b32 v142, v133, v155
	ds_bpermute_b32 v192, v144, v155
	ds_bpermute_b32 v194, v145, v155
	ds_bpermute_b32 v196, v146, v155
	ds_bpermute_b32 v198, v147, v155
	ds_bpermute_b32 v200, v148, v155
	ds_bpermute_b32 v202, v149, v155
	ds_bpermute_b32 v204, v150, v155
	ds_bpermute_b32 v206, v133, v151
	ds_bpermute_b32 v208, v144, v151
	ds_bpermute_b32 v210, v145, v151
	ds_bpermute_b32 v212, v146, v151
	ds_bpermute_b32 v214, v147, v151
	ds_bpermute_b32 v216, v148, v151
	ds_bpermute_b32 v218, v149, v151
	ds_bpermute_b32 v220, v150, v151
	v_cvt_pk_f32_fp8_e32 v[156:157], v40
	v_cvt_pk_f32_fp8_sdwa v[158:159], v40 src0_sel:WORD_1
	v_cvt_pk_f32_fp8_e32 v[160:161], v41
	v_cvt_pk_f32_fp8_sdwa v[162:163], v41 src0_sel:WORD_1
	v_cvt_pk_f32_fp8_e32 v[164:165], v42
	v_cvt_pk_f32_fp8_sdwa v[166:167], v42 src0_sel:WORD_1
	v_cvt_pk_f32_fp8_e32 v[168:169], v43
	v_cvt_pk_f32_fp8_sdwa v[170:171], v43 src0_sel:WORD_1
	v_cvt_pk_f32_fp8_e32 v[172:173], v44
	v_cvt_pk_f32_fp8_sdwa v[174:175], v44 src0_sel:WORD_1
	v_cvt_pk_f32_fp8_e32 v[176:177], v45
	v_cvt_pk_f32_fp8_sdwa v[180:181], v45 src0_sel:WORD_1
	s_waitcnt vmcnt(3) lgkmcnt(15)
	v_pk_fma_f32 v[156:157], v[156:157], v[142:143], 0 op_sel_hi:[1,0,0]
	v_pk_fma_f32 v[158:159], v[158:159], v[142:143], 0 op_sel_hi:[1,0,0]
	v_pk_fma_f32 v[160:161], v[160:161], v[142:143], 0 op_sel_hi:[1,0,0]
	v_pk_fma_f32 v[162:163], v[162:163], v[142:143], 0 op_sel_hi:[1,0,0]
	v_pk_fma_f32 v[164:165], v[164:165], v[142:143], 0 op_sel_hi:[1,0,0]
	v_pk_fma_f32 v[166:167], v[166:167], v[142:143], 0 op_sel_hi:[1,0,0]
	v_pk_fma_f32 v[168:169], v[168:169], v[142:143], 0 op_sel_hi:[1,0,0]
	v_pk_fma_f32 v[170:171], v[170:171], v[142:143], 0 op_sel_hi:[1,0,0]
	s_waitcnt lgkmcnt(14)
	v_pk_fma_f32 v[156:157], v[172:173], v[192:193], v[156:157] op_sel_hi:[1,0,1]
	v_pk_fma_f32 v[158:159], v[174:175], v[192:193], v[158:159] op_sel_hi:[1,0,1]
	v_pk_fma_f32 v[160:161], v[176:177], v[192:193], v[160:161] op_sel_hi:[1,0,1]
	v_pk_fma_f32 v[162:163], v[180:181], v[192:193], v[162:163] op_sel_hi:[1,0,1]
	v_cvt_pk_f32_fp8_e32 v[172:173], v46
	v_cvt_pk_f32_fp8_sdwa v[174:175], v46 src0_sel:WORD_1
	v_cvt_pk_f32_fp8_e32 v[176:177], v47
	v_cvt_pk_f32_fp8_sdwa v[180:181], v47 src0_sel:WORD_1
	v_pk_fma_f32 v[164:165], v[172:173], v[192:193], v[164:165] op_sel_hi:[1,0,1]
	v_pk_fma_f32 v[166:167], v[174:175], v[192:193], v[166:167] op_sel_hi:[1,0,1]
	v_pk_fma_f32 v[168:169], v[176:177], v[192:193], v[168:169] op_sel_hi:[1,0,1]
	v_pk_fma_f32 v[170:171], v[180:181], v[192:193], v[170:171] op_sel_hi:[1,0,1]
	v_cvt_pk_f32_fp8_e32 v[172:173], v64
	v_cvt_pk_f32_fp8_sdwa v[174:175], v64 src0_sel:WORD_1
	v_cvt_pk_f32_fp8_e32 v[176:177], v65
	v_cvt_pk_f32_fp8_sdwa v[180:181], v65 src0_sel:WORD_1
	s_waitcnt lgkmcnt(13)
	v_pk_fma_f32 v[156:157], v[172:173], v[194:195], v[156:157] op_sel_hi:[1,0,1]
	v_pk_fma_f32 v[158:159], v[174:175], v[194:195], v[158:159] op_sel_hi:[1,0,1]
	v_pk_fma_f32 v[160:161], v[176:177], v[194:195], v[160:161] op_sel_hi:[1,0,1]
	v_pk_fma_f32 v[162:163], v[180:181], v[194:195], v[162:163] op_sel_hi:[1,0,1]
	v_cvt_pk_f32_fp8_e32 v[172:173], v66
	v_cvt_pk_f32_fp8_sdwa v[174:175], v66 src0_sel:WORD_1
	v_cvt_pk_f32_fp8_e32 v[176:177], v67
	v_cvt_pk_f32_fp8_sdwa v[180:181], v67 src0_sel:WORD_1
	v_pk_fma_f32 v[164:165], v[172:173], v[194:195], v[164:165] op_sel_hi:[1,0,1]
	v_pk_fma_f32 v[166:167], v[174:175], v[194:195], v[166:167] op_sel_hi:[1,0,1]
	v_pk_fma_f32 v[168:169], v[176:177], v[194:195], v[168:169] op_sel_hi:[1,0,1]
	v_pk_fma_f32 v[170:171], v[180:181], v[194:195], v[170:171] op_sel_hi:[1,0,1]
	v_cvt_pk_f32_fp8_e32 v[172:173], v76
	v_cvt_pk_f32_fp8_sdwa v[174:175], v76 src0_sel:WORD_1
	v_cvt_pk_f32_fp8_e32 v[176:177], v77
	v_cvt_pk_f32_fp8_sdwa v[180:181], v77 src0_sel:WORD_1
	s_waitcnt lgkmcnt(12)
	v_pk_fma_f32 v[156:157], v[172:173], v[196:197], v[156:157] op_sel_hi:[1,0,1]
	v_pk_fma_f32 v[158:159], v[174:175], v[196:197], v[158:159] op_sel_hi:[1,0,1]
	v_pk_fma_f32 v[160:161], v[176:177], v[196:197], v[160:161] op_sel_hi:[1,0,1]
	v_pk_fma_f32 v[162:163], v[180:181], v[196:197], v[162:163] op_sel_hi:[1,0,1]
	v_cvt_pk_f32_fp8_e32 v[172:173], v78
	v_cvt_pk_f32_fp8_sdwa v[174:175], v78 src0_sel:WORD_1
	v_cvt_pk_f32_fp8_e32 v[176:177], v79
	v_cvt_pk_f32_fp8_sdwa v[180:181], v79 src0_sel:WORD_1
	v_pk_fma_f32 v[164:165], v[172:173], v[196:197], v[164:165] op_sel_hi:[1,0,1]
	v_pk_fma_f32 v[166:167], v[174:175], v[196:197], v[166:167] op_sel_hi:[1,0,1]
	v_pk_fma_f32 v[168:169], v[176:177], v[196:197], v[168:169] op_sel_hi:[1,0,1]
	v_pk_fma_f32 v[170:171], v[180:181], v[196:197], v[170:171] op_sel_hi:[1,0,1]
	v_cvt_pk_f32_fp8_e32 v[172:173], v80
	v_cvt_pk_f32_fp8_sdwa v[174:175], v80 src0_sel:WORD_1
	v_cvt_pk_f32_fp8_e32 v[176:177], v81
	v_cvt_pk_f32_fp8_sdwa v[180:181], v81 src0_sel:WORD_1
	s_waitcnt lgkmcnt(11)
	v_pk_fma_f32 v[156:157], v[172:173], v[198:199], v[156:157] op_sel_hi:[1,0,1]
	v_pk_fma_f32 v[158:159], v[174:175], v[198:199], v[158:159] op_sel_hi:[1,0,1]
	v_pk_fma_f32 v[160:161], v[176:177], v[198:199], v[160:161] op_sel_hi:[1,0,1]
	v_pk_fma_f32 v[162:163], v[180:181], v[198:199], v[162:163] op_sel_hi:[1,0,1]
	v_cvt_pk_f32_fp8_e32 v[172:173], v82
	v_cvt_pk_f32_fp8_sdwa v[174:175], v82 src0_sel:WORD_1
	v_cvt_pk_f32_fp8_e32 v[176:177], v83
	v_cvt_pk_f32_fp8_sdwa v[180:181], v83 src0_sel:WORD_1
	v_pk_fma_f32 v[164:165], v[172:173], v[198:199], v[164:165] op_sel_hi:[1,0,1]
	v_pk_fma_f32 v[166:167], v[174:175], v[198:199], v[166:167] op_sel_hi:[1,0,1]
	v_pk_fma_f32 v[168:169], v[176:177], v[198:199], v[168:169] op_sel_hi:[1,0,1]
	v_pk_fma_f32 v[170:171], v[180:181], v[198:199], v[170:171] op_sel_hi:[1,0,1]
	v_cvt_pk_f32_fp8_e32 v[172:173], v84
	v_cvt_pk_f32_fp8_sdwa v[174:175], v84 src0_sel:WORD_1
	v_cvt_pk_f32_fp8_e32 v[176:177], v85
	v_cvt_pk_f32_fp8_sdwa v[180:181], v85 src0_sel:WORD_1
	s_waitcnt lgkmcnt(10)
	v_pk_fma_f32 v[156:157], v[172:173], v[200:201], v[156:157] op_sel_hi:[1,0,1]
	v_pk_fma_f32 v[158:159], v[174:175], v[200:201], v[158:159] op_sel_hi:[1,0,1]
	v_pk_fma_f32 v[160:161], v[176:177], v[200:201], v[160:161] op_sel_hi:[1,0,1]
	v_pk_fma_f32 v[162:163], v[180:181], v[200:201], v[162:163] op_sel_hi:[1,0,1]
	v_cvt_pk_f32_fp8_e32 v[172:173], v86
	v_cvt_pk_f32_fp8_sdwa v[174:175], v86 src0_sel:WORD_1
	v_cvt_pk_f32_fp8_e32 v[176:177], v87
	v_cvt_pk_f32_fp8_sdwa v[180:181], v87 src0_sel:WORD_1
	v_pk_fma_f32 v[164:165], v[172:173], v[200:201], v[164:165] op_sel_hi:[1,0,1]
	v_pk_fma_f32 v[166:167], v[174:175], v[200:201], v[166:167] op_sel_hi:[1,0,1]
	v_pk_fma_f32 v[168:169], v[176:177], v[200:201], v[168:169] op_sel_hi:[1,0,1]
	v_pk_fma_f32 v[170:171], v[180:181], v[200:201], v[170:171] op_sel_hi:[1,0,1]
	v_cvt_pk_f32_fp8_e32 v[172:173], v88
	v_cvt_pk_f32_fp8_sdwa v[174:175], v88 src0_sel:WORD_1
	v_cvt_pk_f32_fp8_e32 v[176:177], v89
	v_cvt_pk_f32_fp8_sdwa v[180:181], v89 src0_sel:WORD_1
	s_waitcnt lgkmcnt(9)
	v_pk_fma_f32 v[156:157], v[172:173], v[202:203], v[156:157] op_sel_hi:[1,0,1]
	v_pk_fma_f32 v[158:159], v[174:175], v[202:203], v[158:159] op_sel_hi:[1,0,1]
	v_pk_fma_f32 v[160:161], v[176:177], v[202:203], v[160:161] op_sel_hi:[1,0,1]
	v_pk_fma_f32 v[162:163], v[180:181], v[202:203], v[162:163] op_sel_hi:[1,0,1]
	v_cvt_pk_f32_fp8_e32 v[172:173], v90
	v_cvt_pk_f32_fp8_sdwa v[174:175], v90 src0_sel:WORD_1
	v_cvt_pk_f32_fp8_e32 v[176:177], v91
	v_cvt_pk_f32_fp8_sdwa v[180:181], v91 src0_sel:WORD_1
	v_pk_fma_f32 v[164:165], v[172:173], v[202:203], v[164:165] op_sel_hi:[1,0,1]
	v_pk_fma_f32 v[166:167], v[174:175], v[202:203], v[166:167] op_sel_hi:[1,0,1]
	v_pk_fma_f32 v[168:169], v[176:177], v[202:203], v[168:169] op_sel_hi:[1,0,1]
	v_pk_fma_f32 v[170:171], v[180:181], v[202:203], v[170:171] op_sel_hi:[1,0,1]
	v_cvt_pk_f32_fp8_e32 v[172:173], v92
	v_cvt_pk_f32_fp8_sdwa v[174:175], v92 src0_sel:WORD_1
	v_cvt_pk_f32_fp8_e32 v[176:177], v93
	v_cvt_pk_f32_fp8_sdwa v[180:181], v93 src0_sel:WORD_1
	s_waitcnt lgkmcnt(8)
	v_pk_fma_f32 v[156:157], v[172:173], v[204:205], v[156:157] op_sel_hi:[1,0,1]
	v_pk_fma_f32 v[158:159], v[174:175], v[204:205], v[158:159] op_sel_hi:[1,0,1]
	v_pk_fma_f32 v[160:161], v[176:177], v[204:205], v[160:161] op_sel_hi:[1,0,1]
	v_pk_fma_f32 v[162:163], v[180:181], v[204:205], v[162:163] op_sel_hi:[1,0,1]
	v_cvt_pk_f32_fp8_e32 v[172:173], v94
	v_cvt_pk_f32_fp8_sdwa v[174:175], v94 src0_sel:WORD_1
	v_cvt_pk_f32_fp8_e32 v[176:177], v95
	v_cvt_pk_f32_fp8_sdwa v[180:181], v95 src0_sel:WORD_1
	v_pk_fma_f32 v[164:165], v[172:173], v[204:205], v[164:165] op_sel_hi:[1,0,1]
	v_pk_fma_f32 v[166:167], v[174:175], v[204:205], v[166:167] op_sel_hi:[1,0,1]
	v_pk_fma_f32 v[168:169], v[176:177], v[204:205], v[168:169] op_sel_hi:[1,0,1]
	v_pk_fma_f32 v[170:171], v[180:181], v[204:205], v[170:171] op_sel_hi:[1,0,1]
	v_cvt_pk_f32_fp8_e32 v[172:173], v96
	v_cvt_pk_f32_fp8_sdwa v[174:175], v96 src0_sel:WORD_1
	v_cvt_pk_f32_fp8_e32 v[176:177], v97
	v_cvt_pk_f32_fp8_sdwa v[180:181], v97 src0_sel:WORD_1
	s_waitcnt lgkmcnt(7)
	v_pk_fma_f32 v[156:157], v[172:173], v[206:207], v[156:157] op_sel_hi:[1,0,1]
	v_pk_fma_f32 v[158:159], v[174:175], v[206:207], v[158:159] op_sel_hi:[1,0,1]
	v_pk_fma_f32 v[160:161], v[176:177], v[206:207], v[160:161] op_sel_hi:[1,0,1]
	v_pk_fma_f32 v[162:163], v[180:181], v[206:207], v[162:163] op_sel_hi:[1,0,1]
	v_cvt_pk_f32_fp8_e32 v[172:173], v98
	v_cvt_pk_f32_fp8_sdwa v[174:175], v98 src0_sel:WORD_1
	v_cvt_pk_f32_fp8_e32 v[176:177], v99
	v_cvt_pk_f32_fp8_sdwa v[180:181], v99 src0_sel:WORD_1
	v_pk_fma_f32 v[164:165], v[172:173], v[206:207], v[164:165] op_sel_hi:[1,0,1]
	v_pk_fma_f32 v[166:167], v[174:175], v[206:207], v[166:167] op_sel_hi:[1,0,1]
	v_pk_fma_f32 v[168:169], v[176:177], v[206:207], v[168:169] op_sel_hi:[1,0,1]
	v_pk_fma_f32 v[170:171], v[180:181], v[206:207], v[170:171] op_sel_hi:[1,0,1]
	v_cvt_pk_f32_fp8_e32 v[172:173], v100
	v_cvt_pk_f32_fp8_sdwa v[174:175], v100 src0_sel:WORD_1
	v_cvt_pk_f32_fp8_e32 v[176:177], v101
	v_cvt_pk_f32_fp8_sdwa v[180:181], v101 src0_sel:WORD_1
	s_waitcnt lgkmcnt(6)
	v_pk_fma_f32 v[156:157], v[172:173], v[208:209], v[156:157] op_sel_hi:[1,0,1]
	v_pk_fma_f32 v[158:159], v[174:175], v[208:209], v[158:159] op_sel_hi:[1,0,1]
	v_pk_fma_f32 v[160:161], v[176:177], v[208:209], v[160:161] op_sel_hi:[1,0,1]
	v_pk_fma_f32 v[162:163], v[180:181], v[208:209], v[162:163] op_sel_hi:[1,0,1]
	v_cvt_pk_f32_fp8_e32 v[172:173], v102
	v_cvt_pk_f32_fp8_sdwa v[174:175], v102 src0_sel:WORD_1
	v_cvt_pk_f32_fp8_e32 v[176:177], v103
	v_cvt_pk_f32_fp8_sdwa v[180:181], v103 src0_sel:WORD_1
	v_pk_fma_f32 v[164:165], v[172:173], v[208:209], v[164:165] op_sel_hi:[1,0,1]
	v_pk_fma_f32 v[166:167], v[174:175], v[208:209], v[166:167] op_sel_hi:[1,0,1]
	v_pk_fma_f32 v[168:169], v[176:177], v[208:209], v[168:169] op_sel_hi:[1,0,1]
	v_pk_fma_f32 v[170:171], v[180:181], v[208:209], v[170:171] op_sel_hi:[1,0,1]
	v_cvt_pk_f32_fp8_e32 v[172:173], v104
	v_cvt_pk_f32_fp8_sdwa v[174:175], v104 src0_sel:WORD_1
	v_cvt_pk_f32_fp8_e32 v[176:177], v105
	v_cvt_pk_f32_fp8_sdwa v[180:181], v105 src0_sel:WORD_1
	s_waitcnt lgkmcnt(5)
	v_pk_fma_f32 v[156:157], v[172:173], v[210:211], v[156:157] op_sel_hi:[1,0,1]
	v_pk_fma_f32 v[158:159], v[174:175], v[210:211], v[158:159] op_sel_hi:[1,0,1]
	v_pk_fma_f32 v[160:161], v[176:177], v[210:211], v[160:161] op_sel_hi:[1,0,1]
	v_pk_fma_f32 v[162:163], v[180:181], v[210:211], v[162:163] op_sel_hi:[1,0,1]
	v_cvt_pk_f32_fp8_e32 v[172:173], v106
	v_cvt_pk_f32_fp8_sdwa v[174:175], v106 src0_sel:WORD_1
	v_cvt_pk_f32_fp8_e32 v[176:177], v107
	v_cvt_pk_f32_fp8_sdwa v[180:181], v107 src0_sel:WORD_1
	v_pk_fma_f32 v[164:165], v[172:173], v[210:211], v[164:165] op_sel_hi:[1,0,1]
	v_pk_fma_f32 v[166:167], v[174:175], v[210:211], v[166:167] op_sel_hi:[1,0,1]
	v_pk_fma_f32 v[168:169], v[176:177], v[210:211], v[168:169] op_sel_hi:[1,0,1]
	v_pk_fma_f32 v[170:171], v[180:181], v[210:211], v[170:171] op_sel_hi:[1,0,1]
	v_cvt_pk_f32_fp8_e32 v[172:173], v108
	v_cvt_pk_f32_fp8_sdwa v[174:175], v108 src0_sel:WORD_1
	v_cvt_pk_f32_fp8_e32 v[176:177], v109
	v_cvt_pk_f32_fp8_sdwa v[180:181], v109 src0_sel:WORD_1
	s_waitcnt lgkmcnt(4)
	v_pk_fma_f32 v[156:157], v[172:173], v[212:213], v[156:157] op_sel_hi:[1,0,1]
	v_pk_fma_f32 v[158:159], v[174:175], v[212:213], v[158:159] op_sel_hi:[1,0,1]
	v_pk_fma_f32 v[160:161], v[176:177], v[212:213], v[160:161] op_sel_hi:[1,0,1]
	v_pk_fma_f32 v[162:163], v[180:181], v[212:213], v[162:163] op_sel_hi:[1,0,1]
	v_cvt_pk_f32_fp8_e32 v[172:173], v110
	v_cvt_pk_f32_fp8_sdwa v[174:175], v110 src0_sel:WORD_1
	v_cvt_pk_f32_fp8_e32 v[176:177], v111
	v_cvt_pk_f32_fp8_sdwa v[180:181], v111 src0_sel:WORD_1
	v_pk_fma_f32 v[164:165], v[172:173], v[212:213], v[164:165] op_sel_hi:[1,0,1]
	v_pk_fma_f32 v[166:167], v[174:175], v[212:213], v[166:167] op_sel_hi:[1,0,1]
	v_pk_fma_f32 v[168:169], v[176:177], v[212:213], v[168:169] op_sel_hi:[1,0,1]
	v_pk_fma_f32 v[170:171], v[180:181], v[212:213], v[170:171] op_sel_hi:[1,0,1]
	v_cvt_pk_f32_fp8_e32 v[172:173], v112
	v_cvt_pk_f32_fp8_sdwa v[174:175], v112 src0_sel:WORD_1
	v_cvt_pk_f32_fp8_e32 v[176:177], v113
	v_cvt_pk_f32_fp8_sdwa v[180:181], v113 src0_sel:WORD_1
	s_waitcnt lgkmcnt(3)
	v_pk_fma_f32 v[156:157], v[172:173], v[214:215], v[156:157] op_sel_hi:[1,0,1]
	v_pk_fma_f32 v[158:159], v[174:175], v[214:215], v[158:159] op_sel_hi:[1,0,1]
	v_pk_fma_f32 v[160:161], v[176:177], v[214:215], v[160:161] op_sel_hi:[1,0,1]
	v_pk_fma_f32 v[162:163], v[180:181], v[214:215], v[162:163] op_sel_hi:[1,0,1]
	v_cvt_pk_f32_fp8_e32 v[172:173], v114
	v_cvt_pk_f32_fp8_sdwa v[174:175], v114 src0_sel:WORD_1
	v_cvt_pk_f32_fp8_e32 v[176:177], v115
	v_cvt_pk_f32_fp8_sdwa v[180:181], v115 src0_sel:WORD_1
	v_pk_fma_f32 v[164:165], v[172:173], v[214:215], v[164:165] op_sel_hi:[1,0,1]
	v_pk_fma_f32 v[166:167], v[174:175], v[214:215], v[166:167] op_sel_hi:[1,0,1]
	v_pk_fma_f32 v[168:169], v[176:177], v[214:215], v[168:169] op_sel_hi:[1,0,1]
	v_pk_fma_f32 v[170:171], v[180:181], v[214:215], v[170:171] op_sel_hi:[1,0,1]
	v_cvt_pk_f32_fp8_e32 v[172:173], v116
	v_cvt_pk_f32_fp8_sdwa v[174:175], v116 src0_sel:WORD_1
	v_cvt_pk_f32_fp8_e32 v[176:177], v117
	v_cvt_pk_f32_fp8_sdwa v[180:181], v117 src0_sel:WORD_1
	s_waitcnt lgkmcnt(2)
	v_pk_fma_f32 v[156:157], v[172:173], v[216:217], v[156:157] op_sel_hi:[1,0,1]
	v_pk_fma_f32 v[158:159], v[174:175], v[216:217], v[158:159] op_sel_hi:[1,0,1]
	v_pk_fma_f32 v[160:161], v[176:177], v[216:217], v[160:161] op_sel_hi:[1,0,1]
	v_pk_fma_f32 v[162:163], v[180:181], v[216:217], v[162:163] op_sel_hi:[1,0,1]
	v_cvt_pk_f32_fp8_e32 v[172:173], v118
	v_cvt_pk_f32_fp8_sdwa v[174:175], v118 src0_sel:WORD_1
	v_cvt_pk_f32_fp8_e32 v[176:177], v119
	v_cvt_pk_f32_fp8_sdwa v[180:181], v119 src0_sel:WORD_1
	v_pk_fma_f32 v[164:165], v[172:173], v[216:217], v[164:165] op_sel_hi:[1,0,1]
	v_pk_fma_f32 v[166:167], v[174:175], v[216:217], v[166:167] op_sel_hi:[1,0,1]
	v_pk_fma_f32 v[168:169], v[176:177], v[216:217], v[168:169] op_sel_hi:[1,0,1]
	v_pk_fma_f32 v[170:171], v[180:181], v[216:217], v[170:171] op_sel_hi:[1,0,1]
	v_cvt_pk_f32_fp8_e32 v[172:173], v120
	v_cvt_pk_f32_fp8_sdwa v[174:175], v120 src0_sel:WORD_1
	v_cvt_pk_f32_fp8_e32 v[176:177], v121
	v_cvt_pk_f32_fp8_sdwa v[180:181], v121 src0_sel:WORD_1
	s_waitcnt lgkmcnt(1)
	v_pk_fma_f32 v[156:157], v[172:173], v[218:219], v[156:157] op_sel_hi:[1,0,1]
	v_pk_fma_f32 v[158:159], v[174:175], v[218:219], v[158:159] op_sel_hi:[1,0,1]
	v_pk_fma_f32 v[160:161], v[176:177], v[218:219], v[160:161] op_sel_hi:[1,0,1]
	v_pk_fma_f32 v[162:163], v[180:181], v[218:219], v[162:163] op_sel_hi:[1,0,1]
	v_cvt_pk_f32_fp8_e32 v[172:173], v122
	v_cvt_pk_f32_fp8_sdwa v[174:175], v122 src0_sel:WORD_1
	v_cvt_pk_f32_fp8_e32 v[176:177], v123
	v_cvt_pk_f32_fp8_sdwa v[180:181], v123 src0_sel:WORD_1
	v_pk_fma_f32 v[164:165], v[172:173], v[218:219], v[164:165] op_sel_hi:[1,0,1]
	v_pk_fma_f32 v[166:167], v[174:175], v[218:219], v[166:167] op_sel_hi:[1,0,1]
	v_pk_fma_f32 v[168:169], v[176:177], v[218:219], v[168:169] op_sel_hi:[1,0,1]
	v_pk_fma_f32 v[170:171], v[180:181], v[218:219], v[170:171] op_sel_hi:[1,0,1]
	v_cvt_pk_f32_fp8_e32 v[172:173], v124
	v_cvt_pk_f32_fp8_sdwa v[174:175], v124 src0_sel:WORD_1
	v_cvt_pk_f32_fp8_e32 v[176:177], v125
	v_cvt_pk_f32_fp8_sdwa v[180:181], v125 src0_sel:WORD_1
	s_waitcnt lgkmcnt(0)
	v_pk_fma_f32 v[156:157], v[172:173], v[220:221], v[156:157] op_sel_hi:[1,0,1]
	v_pk_fma_f32 v[158:159], v[174:175], v[220:221], v[158:159] op_sel_hi:[1,0,1]
	v_pk_fma_f32 v[160:161], v[176:177], v[220:221], v[160:161] op_sel_hi:[1,0,1]
	v_pk_fma_f32 v[162:163], v[180:181], v[220:221], v[162:163] op_sel_hi:[1,0,1]
	v_cvt_pk_f32_fp8_e32 v[172:173], v126
	v_cvt_pk_f32_fp8_sdwa v[174:175], v126 src0_sel:WORD_1
	v_cvt_pk_f32_fp8_e32 v[176:177], v127
	v_cvt_pk_f32_fp8_sdwa v[180:181], v127 src0_sel:WORD_1
	v_pk_fma_f32 v[164:165], v[172:173], v[220:221], v[164:165] op_sel_hi:[1,0,1]
	v_pk_fma_f32 v[166:167], v[174:175], v[220:221], v[166:167] op_sel_hi:[1,0,1]
	v_pk_fma_f32 v[168:169], v[176:177], v[220:221], v[168:169] op_sel_hi:[1,0,1]
	v_pk_fma_f32 v[170:171], v[180:181], v[220:221], v[170:171] op_sel_hi:[1,0,1]
	v_permlane32_swap_b32_e32 v156, v164
	v_permlane32_swap_b32_e32 v157, v165
	v_permlane32_swap_b32_e32 v158, v166
	v_permlane32_swap_b32_e32 v159, v167
	v_permlane32_swap_b32_e32 v160, v168
	v_permlane32_swap_b32_e32 v161, v169
	v_permlane32_swap_b32_e32 v162, v170
	v_permlane32_swap_b32_e32 v163, v171
	v_add_f32_e32 v156, v156, v164
	v_add_f32_e32 v157, v157, v165
	v_add_f32_e32 v158, v158, v166
	v_add_f32_e32 v159, v159, v167
	v_add_f32_e32 v160, v160, v168
	v_add_f32_e32 v161, v161, v169
	v_add_f32_e32 v162, v162, v170
	v_add_f32_e32 v163, v163, v171
	v_permlane16_swap_b32_e32 v156, v160
	v_permlane16_swap_b32_e32 v157, v161
	v_permlane16_swap_b32_e32 v158, v162
	v_permlane16_swap_b32_e32 v159, v163
	v_pk_add_f32 v[156:157], v[156:157], v[160:161]
	v_pk_add_f32 v[158:159], v[158:159], v[162:163]
	v_lshlrev_b64 v[164:165], 10, v[138:139]
	v_cndmask_b32_e32 v142, v156, v158, vcc
	v_cndmask_b32_e32 v163, v159, v157, vcc
	v_cndmask_b32_e32 v162, v158, v156, vcc
	v_mov_b32_dpp v160, v142 row_ror:8 row_mask:0xf bank_mask:0xf bound_ctrl:1
	v_cndmask_b32_e32 v142, v157, v159, vcc
	v_or_b32_e32 v164, v164, v132
	v_lshl_add_u64 v[166:167], v[164:165], 2, s[70:71]
	v_mov_b32_dpp v161, v142 row_ror:8 row_mask:0xf bank_mask:0xf bound_ctrl:1
	v_pk_add_f32 v[156:157], v[162:163], v[160:161]
	v_lshl_add_u64 v[158:159], v[164:165], 1, s[12:13]
	v_pk_add_f32 v[156:157], v[136:137], v[156:157]
	global_store_dwordx2 v[166:167], v[156:157], off
	v_cvt_pk_bf16_f32 v142, v156, v157
	v_pk_mul_f32 v[156:157], v[156:157], v[156:157]
	global_store_dword v[158:159], v142, off
	v_add_f32_e32 v142, v156, v157
	s_nop 1
	v_add_f32_dpp v142, v142, v142 quad_perm:[1,0,3,2] row_mask:0xf bank_mask:0xf bound_ctrl:1
	s_nop 1
	v_add_f32_dpp v142, v142, v142 quad_perm:[2,3,0,1] row_mask:0xf bank_mask:0xf bound_ctrl:1
	s_nop 1
	v_add_f32_dpp v142, v142, v142 row_ror:4 row_mask:0xf bank_mask:0xf bound_ctrl:1
	s_nop 1
	v_add_f32_dpp v142, v142, v142 row_ror:8 row_mask:0xf bank_mask:0xf bound_ctrl:1
	v_mov_b32_e32 v151, v142
	s_nop 1
	v_permlane16_swap_b32_e32 v142, v151
	v_add_f32_e32 v142, v142, v151
	v_mov_b32_e32 v151, v142
	s_nop 1
	v_permlane32_swap_b32_e32 v142, v151
	s_and_saveexec_b64 s[0:1], s[4:5]
	s_cbranch_execz .LBB0_658
	v_lshlrev_b64 v[156:157], 5, v[138:139]
	v_add_f32_e32 v142, v142, v151
	v_lshl_add_u64 v[156:157], s[18:19], 0, v[156:157]
	global_store_dword v[156:157], v142, off
	s_branch .LBB0_658

.LBB0_1247:
	s_or_b64 exec, exec, s[16:17]
	v_add_u32_e32 v142, s22, v140
	v_min_i32_e32 v154, 0x3fff, v142
	v_ashrrev_i32_e32 v155, 31, v154
	v_lshlrev_b64 v[154:155], 9, v[154:155]
	v_lshl_or_b32 v154, v128, 2, v154
	v_lshl_add_u64 v[160:161], s[10:11], 0, v[154:155]
	v_or_b32_e32 v162, 0x100, v154
	v_mov_b32_e32 v163, v155
	v_lshl_add_u64 v[154:155], s[12:13], 0, v[154:155]
	v_lshl_add_u64 v[164:165], s[10:11], 0, v[162:163]
	v_lshl_add_u64 v[162:163], s[12:13], 0, v[162:163]
	global_load_dword v158, v[160:161], off
	global_load_dword v157, v[164:165], off
	s_nop 0
	global_load_dword v154, v[154:155], off
	s_nop 0
	global_load_dword v155, v[162:163], off
	s_waitcnt vmcnt(21)
	ds_bpermute_b32 v160, v133, v159
	ds_bpermute_b32 v192, v144, v159
	ds_bpermute_b32 v194, v145, v159
	ds_bpermute_b32 v196, v146, v159
	ds_bpermute_b32 v198, v147, v159
	ds_bpermute_b32 v200, v148, v159
	ds_bpermute_b32 v202, v149, v159
	ds_bpermute_b32 v204, v150, v159
	ds_bpermute_b32 v206, v133, v156
	ds_bpermute_b32 v208, v144, v156
	ds_bpermute_b32 v210, v145, v156
	ds_bpermute_b32 v212, v146, v156
	ds_bpermute_b32 v214, v147, v156
	ds_bpermute_b32 v216, v148, v156
	ds_bpermute_b32 v218, v149, v156
	ds_bpermute_b32 v220, v150, v156
	s_waitcnt vmcnt(5)
	v_cvt_pk_f32_fp8_e32 v[162:163], v12
	v_cvt_pk_f32_fp8_sdwa v[164:165], v12 src0_sel:WORD_1
	v_cvt_pk_f32_fp8_e32 v[166:167], v13
	v_cvt_pk_f32_fp8_sdwa v[168:169], v13 src0_sel:WORD_1
	v_cvt_pk_f32_fp8_e32 v[170:171], v14
	v_cvt_pk_f32_fp8_sdwa v[172:173], v14 src0_sel:WORD_1
	v_cvt_pk_f32_fp8_e32 v[174:175], v15
	v_cvt_pk_f32_fp8_sdwa v[176:177], v15 src0_sel:WORD_1
	s_waitcnt lgkmcnt(15)
	v_pk_fma_f32 v[162:163], v[162:163], v[160:161], 0 op_sel_hi:[1,0,0]
	v_pk_fma_f32 v[164:165], v[164:165], v[160:161], 0 op_sel_hi:[1,0,0]
	v_pk_fma_f32 v[166:167], v[166:167], v[160:161], 0 op_sel_hi:[1,0,0]
	v_pk_fma_f32 v[168:169], v[168:169], v[160:161], 0 op_sel_hi:[1,0,0]
	v_pk_fma_f32 v[170:171], v[170:171], v[160:161], 0 op_sel_hi:[1,0,0]
	v_pk_fma_f32 v[172:173], v[172:173], v[160:161], 0 op_sel_hi:[1,0,0]
	v_pk_fma_f32 v[174:175], v[174:175], v[160:161], 0 op_sel_hi:[1,0,0]
	v_pk_fma_f32 v[160:161], v[176:177], v[160:161], 0 op_sel_hi:[1,0,0]
	v_cvt_pk_f32_fp8_e32 v[178:179], v8
	v_cvt_pk_f32_fp8_sdwa v[180:181], v8 src0_sel:WORD_1
	v_cvt_pk_f32_fp8_e32 v[182:183], v9
	v_cvt_pk_f32_fp8_sdwa v[184:185], v9 src0_sel:WORD_1
	s_waitcnt lgkmcnt(14)
	v_pk_fma_f32 v[162:163], v[178:179], v[192:193], v[162:163] op_sel_hi:[1,0,1]
	v_pk_fma_f32 v[164:165], v[180:181], v[192:193], v[164:165] op_sel_hi:[1,0,1]
	v_pk_fma_f32 v[166:167], v[182:183], v[192:193], v[166:167] op_sel_hi:[1,0,1]
	v_pk_fma_f32 v[168:169], v[184:185], v[192:193], v[168:169] op_sel_hi:[1,0,1]
	v_cvt_pk_f32_fp8_e32 v[178:179], v10
	v_cvt_pk_f32_fp8_sdwa v[180:181], v10 src0_sel:WORD_1
	v_cvt_pk_f32_fp8_e32 v[182:183], v11
	v_cvt_pk_f32_fp8_sdwa v[184:185], v11 src0_sel:WORD_1
	v_pk_fma_f32 v[170:171], v[178:179], v[192:193], v[170:171] op_sel_hi:[1,0,1]
	v_pk_fma_f32 v[172:173], v[180:181], v[192:193], v[172:173] op_sel_hi:[1,0,1]
	v_pk_fma_f32 v[174:175], v[182:183], v[192:193], v[174:175] op_sel_hi:[1,0,1]
	v_pk_fma_f32 v[160:161], v[184:185], v[192:193], v[160:161] op_sel_hi:[1,0,1]
	v_cvt_pk_f32_fp8_e32 v[178:179], v4
	v_cvt_pk_f32_fp8_sdwa v[180:181], v4 src0_sel:WORD_1
	v_cvt_pk_f32_fp8_e32 v[182:183], v5
	v_cvt_pk_f32_fp8_sdwa v[184:185], v5 src0_sel:WORD_1
	s_waitcnt lgkmcnt(13)
	v_pk_fma_f32 v[162:163], v[178:179], v[194:195], v[162:163] op_sel_hi:[1,0,1]
	v_pk_fma_f32 v[164:165], v[180:181], v[194:195], v[164:165] op_sel_hi:[1,0,1]
	v_pk_fma_f32 v[166:167], v[182:183], v[194:195], v[166:167] op_sel_hi:[1,0,1]
	v_pk_fma_f32 v[168:169], v[184:185], v[194:195], v[168:169] op_sel_hi:[1,0,1]
	v_cvt_pk_f32_fp8_e32 v[178:179], v6
	v_cvt_pk_f32_fp8_sdwa v[180:181], v6 src0_sel:WORD_1
	v_cvt_pk_f32_fp8_e32 v[182:183], v7
	v_cvt_pk_f32_fp8_sdwa v[184:185], v7 src0_sel:WORD_1
	v_pk_fma_f32 v[170:171], v[178:179], v[194:195], v[170:171] op_sel_hi:[1,0,1]
	v_pk_fma_f32 v[172:173], v[180:181], v[194:195], v[172:173] op_sel_hi:[1,0,1]
	v_pk_fma_f32 v[174:175], v[182:183], v[194:195], v[174:175] op_sel_hi:[1,0,1]
	v_pk_fma_f32 v[160:161], v[184:185], v[194:195], v[160:161] op_sel_hi:[1,0,1]
	v_cvt_pk_f32_fp8_e32 v[178:179], v0
	v_cvt_pk_f32_fp8_sdwa v[180:181], v0 src0_sel:WORD_1
	v_cvt_pk_f32_fp8_e32 v[182:183], v1
	v_cvt_pk_f32_fp8_sdwa v[184:185], v1 src0_sel:WORD_1
	s_waitcnt lgkmcnt(12)
	v_pk_fma_f32 v[162:163], v[178:179], v[196:197], v[162:163] op_sel_hi:[1,0,1]
	v_pk_fma_f32 v[164:165], v[180:181], v[196:197], v[164:165] op_sel_hi:[1,0,1]
	v_pk_fma_f32 v[166:167], v[182:183], v[196:197], v[166:167] op_sel_hi:[1,0,1]
	v_pk_fma_f32 v[168:169], v[184:185], v[196:197], v[168:169] op_sel_hi:[1,0,1]
	v_cvt_pk_f32_fp8_e32 v[178:179], v2
	v_cvt_pk_f32_fp8_sdwa v[180:181], v2 src0_sel:WORD_1
	v_cvt_pk_f32_fp8_e32 v[182:183], v3
	v_cvt_pk_f32_fp8_sdwa v[184:185], v3 src0_sel:WORD_1
	v_pk_fma_f32 v[170:171], v[178:179], v[196:197], v[170:171] op_sel_hi:[1,0,1]
	v_pk_fma_f32 v[172:173], v[180:181], v[196:197], v[172:173] op_sel_hi:[1,0,1]
	v_pk_fma_f32 v[174:175], v[182:183], v[196:197], v[174:175] op_sel_hi:[1,0,1]
	v_pk_fma_f32 v[160:161], v[184:185], v[196:197], v[160:161] op_sel_hi:[1,0,1]
	v_cvt_pk_f32_fp8_e32 v[178:179], v20
	v_cvt_pk_f32_fp8_sdwa v[180:181], v20 src0_sel:WORD_1
	v_cvt_pk_f32_fp8_e32 v[182:183], v21
	v_cvt_pk_f32_fp8_sdwa v[184:185], v21 src0_sel:WORD_1
	s_waitcnt lgkmcnt(11)
	v_pk_fma_f32 v[162:163], v[178:179], v[198:199], v[162:163] op_sel_hi:[1,0,1]
	v_pk_fma_f32 v[164:165], v[180:181], v[198:199], v[164:165] op_sel_hi:[1,0,1]
	v_pk_fma_f32 v[166:167], v[182:183], v[198:199], v[166:167] op_sel_hi:[1,0,1]
	v_pk_fma_f32 v[168:169], v[184:185], v[198:199], v[168:169] op_sel_hi:[1,0,1]
	v_cvt_pk_f32_fp8_e32 v[178:179], v22
	v_cvt_pk_f32_fp8_sdwa v[180:181], v22 src0_sel:WORD_1
	v_cvt_pk_f32_fp8_e32 v[182:183], v23
	v_cvt_pk_f32_fp8_sdwa v[184:185], v23 src0_sel:WORD_1
	v_pk_fma_f32 v[170:171], v[178:179], v[198:199], v[170:171] op_sel_hi:[1,0,1]
	v_pk_fma_f32 v[172:173], v[180:181], v[198:199], v[172:173] op_sel_hi:[1,0,1]
	v_pk_fma_f32 v[174:175], v[182:183], v[198:199], v[174:175] op_sel_hi:[1,0,1]
	v_pk_fma_f32 v[160:161], v[184:185], v[198:199], v[160:161] op_sel_hi:[1,0,1]
	v_cvt_pk_f32_fp8_e32 v[178:179], v16
	v_cvt_pk_f32_fp8_sdwa v[180:181], v16 src0_sel:WORD_1
	v_cvt_pk_f32_fp8_e32 v[182:183], v17
	v_cvt_pk_f32_fp8_sdwa v[184:185], v17 src0_sel:WORD_1
	s_waitcnt lgkmcnt(10)
	v_pk_fma_f32 v[162:163], v[178:179], v[200:201], v[162:163] op_sel_hi:[1,0,1]
	v_pk_fma_f32 v[164:165], v[180:181], v[200:201], v[164:165] op_sel_hi:[1,0,1]
	v_pk_fma_f32 v[166:167], v[182:183], v[200:201], v[166:167] op_sel_hi:[1,0,1]
	v_pk_fma_f32 v[168:169], v[184:185], v[200:201], v[168:169] op_sel_hi:[1,0,1]
	v_cvt_pk_f32_fp8_e32 v[178:179], v18
	v_cvt_pk_f32_fp8_sdwa v[180:181], v18 src0_sel:WORD_1
	v_cvt_pk_f32_fp8_e32 v[182:183], v19
	v_cvt_pk_f32_fp8_sdwa v[184:185], v19 src0_sel:WORD_1
	v_pk_fma_f32 v[170:171], v[178:179], v[200:201], v[170:171] op_sel_hi:[1,0,1]
	v_pk_fma_f32 v[172:173], v[180:181], v[200:201], v[172:173] op_sel_hi:[1,0,1]
	v_pk_fma_f32 v[174:175], v[182:183], v[200:201], v[174:175] op_sel_hi:[1,0,1]
	v_pk_fma_f32 v[160:161], v[184:185], v[200:201], v[160:161] op_sel_hi:[1,0,1]
	v_cvt_pk_f32_fp8_e32 v[178:179], v28
	v_cvt_pk_f32_fp8_sdwa v[180:181], v28 src0_sel:WORD_1
	v_cvt_pk_f32_fp8_e32 v[182:183], v29
	v_cvt_pk_f32_fp8_sdwa v[184:185], v29 src0_sel:WORD_1
	s_waitcnt lgkmcnt(9)
	v_pk_fma_f32 v[162:163], v[178:179], v[202:203], v[162:163] op_sel_hi:[1,0,1]
	v_pk_fma_f32 v[164:165], v[180:181], v[202:203], v[164:165] op_sel_hi:[1,0,1]
	v_pk_fma_f32 v[166:167], v[182:183], v[202:203], v[166:167] op_sel_hi:[1,0,1]
	v_pk_fma_f32 v[168:169], v[184:185], v[202:203], v[168:169] op_sel_hi:[1,0,1]
	v_cvt_pk_f32_fp8_e32 v[178:179], v30
	v_cvt_pk_f32_fp8_sdwa v[180:181], v30 src0_sel:WORD_1
	v_cvt_pk_f32_fp8_e32 v[182:183], v31
	v_cvt_pk_f32_fp8_sdwa v[184:185], v31 src0_sel:WORD_1
	v_pk_fma_f32 v[170:171], v[178:179], v[202:203], v[170:171] op_sel_hi:[1,0,1]
	v_pk_fma_f32 v[172:173], v[180:181], v[202:203], v[172:173] op_sel_hi:[1,0,1]
	v_pk_fma_f32 v[174:175], v[182:183], v[202:203], v[174:175] op_sel_hi:[1,0,1]
	v_pk_fma_f32 v[160:161], v[184:185], v[202:203], v[160:161] op_sel_hi:[1,0,1]
	v_cvt_pk_f32_fp8_e32 v[178:179], v24
	v_cvt_pk_f32_fp8_sdwa v[180:181], v24 src0_sel:WORD_1
	v_cvt_pk_f32_fp8_e32 v[182:183], v25
	v_cvt_pk_f32_fp8_sdwa v[184:185], v25 src0_sel:WORD_1
	s_waitcnt lgkmcnt(8)
	v_pk_fma_f32 v[162:163], v[178:179], v[204:205], v[162:163] op_sel_hi:[1,0,1]
	v_pk_fma_f32 v[164:165], v[180:181], v[204:205], v[164:165] op_sel_hi:[1,0,1]
	v_pk_fma_f32 v[166:167], v[182:183], v[204:205], v[166:167] op_sel_hi:[1,0,1]
	v_pk_fma_f32 v[168:169], v[184:185], v[204:205], v[168:169] op_sel_hi:[1,0,1]
	v_cvt_pk_f32_fp8_e32 v[178:179], v26
	v_cvt_pk_f32_fp8_sdwa v[180:181], v26 src0_sel:WORD_1
	v_cvt_pk_f32_fp8_e32 v[182:183], v27
	v_cvt_pk_f32_fp8_sdwa v[184:185], v27 src0_sel:WORD_1
	v_pk_fma_f32 v[170:171], v[178:179], v[204:205], v[170:171] op_sel_hi:[1,0,1]
	v_pk_fma_f32 v[172:173], v[180:181], v[204:205], v[172:173] op_sel_hi:[1,0,1]
	v_pk_fma_f32 v[174:175], v[182:183], v[204:205], v[174:175] op_sel_hi:[1,0,1]
	v_pk_fma_f32 v[160:161], v[184:185], v[204:205], v[160:161] op_sel_hi:[1,0,1]
	v_cvt_pk_f32_fp8_e32 v[178:179], v36
	v_cvt_pk_f32_fp8_sdwa v[180:181], v36 src0_sel:WORD_1
	v_cvt_pk_f32_fp8_e32 v[182:183], v37
	v_cvt_pk_f32_fp8_sdwa v[184:185], v37 src0_sel:WORD_1
	s_waitcnt lgkmcnt(7)
	v_pk_fma_f32 v[162:163], v[178:179], v[206:207], v[162:163] op_sel_hi:[1,0,1]
	v_pk_fma_f32 v[164:165], v[180:181], v[206:207], v[164:165] op_sel_hi:[1,0,1]
	v_pk_fma_f32 v[166:167], v[182:183], v[206:207], v[166:167] op_sel_hi:[1,0,1]
	v_pk_fma_f32 v[168:169], v[184:185], v[206:207], v[168:169] op_sel_hi:[1,0,1]
	v_cvt_pk_f32_fp8_e32 v[178:179], v38
	v_cvt_pk_f32_fp8_sdwa v[180:181], v38 src0_sel:WORD_1
	v_cvt_pk_f32_fp8_e32 v[182:183], v39
	v_cvt_pk_f32_fp8_sdwa v[184:185], v39 src0_sel:WORD_1
	v_pk_fma_f32 v[170:171], v[178:179], v[206:207], v[170:171] op_sel_hi:[1,0,1]
	v_pk_fma_f32 v[172:173], v[180:181], v[206:207], v[172:173] op_sel_hi:[1,0,1]
	v_pk_fma_f32 v[174:175], v[182:183], v[206:207], v[174:175] op_sel_hi:[1,0,1]
	v_pk_fma_f32 v[160:161], v[184:185], v[206:207], v[160:161] op_sel_hi:[1,0,1]
	v_cvt_pk_f32_fp8_e32 v[178:179], v32
	v_cvt_pk_f32_fp8_sdwa v[180:181], v32 src0_sel:WORD_1
	v_cvt_pk_f32_fp8_e32 v[182:183], v33
	v_cvt_pk_f32_fp8_sdwa v[184:185], v33 src0_sel:WORD_1
	s_waitcnt lgkmcnt(6)
	v_pk_fma_f32 v[162:163], v[178:179], v[208:209], v[162:163] op_sel_hi:[1,0,1]
	v_pk_fma_f32 v[164:165], v[180:181], v[208:209], v[164:165] op_sel_hi:[1,0,1]
	v_pk_fma_f32 v[166:167], v[182:183], v[208:209], v[166:167] op_sel_hi:[1,0,1]
	v_pk_fma_f32 v[168:169], v[184:185], v[208:209], v[168:169] op_sel_hi:[1,0,1]
	v_cvt_pk_f32_fp8_e32 v[178:179], v34
	v_cvt_pk_f32_fp8_sdwa v[180:181], v34 src0_sel:WORD_1
	v_cvt_pk_f32_fp8_e32 v[182:183], v35
	v_cvt_pk_f32_fp8_sdwa v[184:185], v35 src0_sel:WORD_1
	v_pk_fma_f32 v[170:171], v[178:179], v[208:209], v[170:171] op_sel_hi:[1,0,1]
	v_pk_fma_f32 v[172:173], v[180:181], v[208:209], v[172:173] op_sel_hi:[1,0,1]
	v_pk_fma_f32 v[174:175], v[182:183], v[208:209], v[174:175] op_sel_hi:[1,0,1]
	v_pk_fma_f32 v[160:161], v[184:185], v[208:209], v[160:161] op_sel_hi:[1,0,1]
	v_cvt_pk_f32_fp8_e32 v[178:179], v44
	v_cvt_pk_f32_fp8_sdwa v[180:181], v44 src0_sel:WORD_1
	v_cvt_pk_f32_fp8_e32 v[182:183], v45
	v_cvt_pk_f32_fp8_sdwa v[184:185], v45 src0_sel:WORD_1
	s_waitcnt lgkmcnt(5)
	v_pk_fma_f32 v[162:163], v[178:179], v[210:211], v[162:163] op_sel_hi:[1,0,1]
	v_pk_fma_f32 v[164:165], v[180:181], v[210:211], v[164:165] op_sel_hi:[1,0,1]
	v_pk_fma_f32 v[166:167], v[182:183], v[210:211], v[166:167] op_sel_hi:[1,0,1]
	v_pk_fma_f32 v[168:169], v[184:185], v[210:211], v[168:169] op_sel_hi:[1,0,1]
	v_cvt_pk_f32_fp8_e32 v[178:179], v46
	v_cvt_pk_f32_fp8_sdwa v[180:181], v46 src0_sel:WORD_1
	v_cvt_pk_f32_fp8_e32 v[182:183], v47
	v_cvt_pk_f32_fp8_sdwa v[184:185], v47 src0_sel:WORD_1
	v_pk_fma_f32 v[170:171], v[178:179], v[210:211], v[170:171] op_sel_hi:[1,0,1]
	v_pk_fma_f32 v[172:173], v[180:181], v[210:211], v[172:173] op_sel_hi:[1,0,1]
	v_pk_fma_f32 v[174:175], v[182:183], v[210:211], v[174:175] op_sel_hi:[1,0,1]
	v_pk_fma_f32 v[160:161], v[184:185], v[210:211], v[160:161] op_sel_hi:[1,0,1]
	v_cvt_pk_f32_fp8_e32 v[178:179], v40
	v_cvt_pk_f32_fp8_sdwa v[180:181], v40 src0_sel:WORD_1
	v_cvt_pk_f32_fp8_e32 v[182:183], v41
	v_cvt_pk_f32_fp8_sdwa v[184:185], v41 src0_sel:WORD_1
	s_waitcnt lgkmcnt(4)
	v_pk_fma_f32 v[162:163], v[178:179], v[212:213], v[162:163] op_sel_hi:[1,0,1]
	v_pk_fma_f32 v[164:165], v[180:181], v[212:213], v[164:165] op_sel_hi:[1,0,1]
	v_pk_fma_f32 v[166:167], v[182:183], v[212:213], v[166:167] op_sel_hi:[1,0,1]
	v_pk_fma_f32 v[168:169], v[184:185], v[212:213], v[168:169] op_sel_hi:[1,0,1]
	v_cvt_pk_f32_fp8_e32 v[178:179], v42
	v_cvt_pk_f32_fp8_sdwa v[180:181], v42 src0_sel:WORD_1
	v_cvt_pk_f32_fp8_e32 v[182:183], v43
	v_cvt_pk_f32_fp8_sdwa v[184:185], v43 src0_sel:WORD_1
	v_pk_fma_f32 v[170:171], v[178:179], v[212:213], v[170:171] op_sel_hi:[1,0,1]
	v_pk_fma_f32 v[172:173], v[180:181], v[212:213], v[172:173] op_sel_hi:[1,0,1]
	v_pk_fma_f32 v[174:175], v[182:183], v[212:213], v[174:175] op_sel_hi:[1,0,1]
	v_pk_fma_f32 v[160:161], v[184:185], v[212:213], v[160:161] op_sel_hi:[1,0,1]
	v_cvt_pk_f32_fp8_e32 v[178:179], v60
	v_cvt_pk_f32_fp8_sdwa v[180:181], v60 src0_sel:WORD_1
	v_cvt_pk_f32_fp8_e32 v[182:183], v61
	v_cvt_pk_f32_fp8_sdwa v[184:185], v61 src0_sel:WORD_1
	s_waitcnt lgkmcnt(3)
	v_pk_fma_f32 v[162:163], v[178:179], v[214:215], v[162:163] op_sel_hi:[1,0,1]
	v_pk_fma_f32 v[164:165], v[180:181], v[214:215], v[164:165] op_sel_hi:[1,0,1]
	v_pk_fma_f32 v[166:167], v[182:183], v[214:215], v[166:167] op_sel_hi:[1,0,1]
	v_pk_fma_f32 v[168:169], v[184:185], v[214:215], v[168:169] op_sel_hi:[1,0,1]
	v_cvt_pk_f32_fp8_e32 v[178:179], v62
	v_cvt_pk_f32_fp8_sdwa v[180:181], v62 src0_sel:WORD_1
	v_cvt_pk_f32_fp8_e32 v[182:183], v63
	v_cvt_pk_f32_fp8_sdwa v[184:185], v63 src0_sel:WORD_1
	v_pk_fma_f32 v[170:171], v[178:179], v[214:215], v[170:171] op_sel_hi:[1,0,1]
	v_pk_fma_f32 v[172:173], v[180:181], v[214:215], v[172:173] op_sel_hi:[1,0,1]
	v_pk_fma_f32 v[174:175], v[182:183], v[214:215], v[174:175] op_sel_hi:[1,0,1]
	v_pk_fma_f32 v[160:161], v[184:185], v[214:215], v[160:161] op_sel_hi:[1,0,1]
	v_cvt_pk_f32_fp8_e32 v[178:179], v56
	v_cvt_pk_f32_fp8_sdwa v[180:181], v56 src0_sel:WORD_1
	v_cvt_pk_f32_fp8_e32 v[182:183], v57
	v_cvt_pk_f32_fp8_sdwa v[184:185], v57 src0_sel:WORD_1
	s_waitcnt lgkmcnt(2)
	v_pk_fma_f32 v[162:163], v[178:179], v[216:217], v[162:163] op_sel_hi:[1,0,1]
	v_pk_fma_f32 v[164:165], v[180:181], v[216:217], v[164:165] op_sel_hi:[1,0,1]
	v_pk_fma_f32 v[166:167], v[182:183], v[216:217], v[166:167] op_sel_hi:[1,0,1]
	v_pk_fma_f32 v[168:169], v[184:185], v[216:217], v[168:169] op_sel_hi:[1,0,1]
	v_cvt_pk_f32_fp8_e32 v[178:179], v58
	v_cvt_pk_f32_fp8_sdwa v[180:181], v58 src0_sel:WORD_1
	v_cvt_pk_f32_fp8_e32 v[182:183], v59
	v_cvt_pk_f32_fp8_sdwa v[184:185], v59 src0_sel:WORD_1
	v_pk_fma_f32 v[170:171], v[178:179], v[216:217], v[170:171] op_sel_hi:[1,0,1]
	v_pk_fma_f32 v[172:173], v[180:181], v[216:217], v[172:173] op_sel_hi:[1,0,1]
	v_pk_fma_f32 v[174:175], v[182:183], v[216:217], v[174:175] op_sel_hi:[1,0,1]
	v_pk_fma_f32 v[160:161], v[184:185], v[216:217], v[160:161] op_sel_hi:[1,0,1]
	v_cvt_pk_f32_fp8_e32 v[178:179], v68
	v_cvt_pk_f32_fp8_sdwa v[180:181], v68 src0_sel:WORD_1
	v_cvt_pk_f32_fp8_e32 v[182:183], v69
	v_cvt_pk_f32_fp8_sdwa v[184:185], v69 src0_sel:WORD_1
	s_waitcnt lgkmcnt(1)
	v_pk_fma_f32 v[162:163], v[178:179], v[218:219], v[162:163] op_sel_hi:[1,0,1]
	v_pk_fma_f32 v[164:165], v[180:181], v[218:219], v[164:165] op_sel_hi:[1,0,1]
	v_pk_fma_f32 v[166:167], v[182:183], v[218:219], v[166:167] op_sel_hi:[1,0,1]
	v_pk_fma_f32 v[168:169], v[184:185], v[218:219], v[168:169] op_sel_hi:[1,0,1]
	v_cvt_pk_f32_fp8_e32 v[178:179], v70
	v_cvt_pk_f32_fp8_sdwa v[180:181], v70 src0_sel:WORD_1
	v_cvt_pk_f32_fp8_e32 v[182:183], v71
	v_cvt_pk_f32_fp8_sdwa v[184:185], v71 src0_sel:WORD_1
	v_pk_fma_f32 v[170:171], v[178:179], v[218:219], v[170:171] op_sel_hi:[1,0,1]
	v_pk_fma_f32 v[172:173], v[180:181], v[218:219], v[172:173] op_sel_hi:[1,0,1]
	v_pk_fma_f32 v[174:175], v[182:183], v[218:219], v[174:175] op_sel_hi:[1,0,1]
	v_pk_fma_f32 v[160:161], v[184:185], v[218:219], v[160:161] op_sel_hi:[1,0,1]
	v_cvt_pk_f32_fp8_e32 v[176:177], v64
	v_cvt_pk_f32_fp8_sdwa v[178:179], v64 src0_sel:WORD_1
	v_cvt_pk_f32_fp8_e32 v[180:181], v65
	v_cvt_pk_f32_fp8_sdwa v[182:183], v65 src0_sel:WORD_1
	s_waitcnt vmcnt(2) lgkmcnt(0)
	v_pk_fma_f32 v[162:163], v[176:177], v[220:221], v[162:163] op_sel_hi:[1,0,1]
	v_pk_fma_f32 v[164:165], v[178:179], v[220:221], v[164:165] op_sel_hi:[1,0,1]
	v_pk_fma_f32 v[166:167], v[180:181], v[220:221], v[166:167] op_sel_hi:[1,0,1]
	v_pk_fma_f32 v[168:169], v[182:183], v[220:221], v[168:169] op_sel_hi:[1,0,1]
	v_cvt_pk_f32_fp8_e32 v[176:177], v66
	v_cvt_pk_f32_fp8_sdwa v[178:179], v66 src0_sel:WORD_1
	v_cvt_pk_f32_fp8_e32 v[180:181], v67
	v_cvt_pk_f32_fp8_sdwa v[182:183], v67 src0_sel:WORD_1
	v_pk_fma_f32 v[170:171], v[176:177], v[220:221], v[170:171] op_sel_hi:[1,0,1]
	v_pk_fma_f32 v[172:173], v[178:179], v[220:221], v[172:173] op_sel_hi:[1,0,1]
	v_pk_fma_f32 v[174:175], v[180:181], v[220:221], v[174:175] op_sel_hi:[1,0,1]
	v_pk_fma_f32 v[160:161], v[182:183], v[220:221], v[160:161] op_sel_hi:[1,0,1]
	v_permlane32_swap_b32_e32 v162, v170
	v_permlane32_swap_b32_e32 v163, v171
	v_permlane32_swap_b32_e32 v164, v172
	v_permlane32_swap_b32_e32 v165, v173
	v_permlane32_swap_b32_e32 v166, v174
	v_permlane32_swap_b32_e32 v167, v175
	v_permlane32_swap_b32_e32 v168, v160
	v_permlane32_swap_b32_e32 v169, v161
	v_add_f32_e32 v162, v162, v170
	v_add_f32_e32 v163, v163, v171
	v_add_f32_e32 v164, v164, v172
	v_add_f32_e32 v165, v165, v173
	v_add_f32_e32 v166, v166, v174
	v_add_f32_e32 v167, v167, v175
	v_add_f32_e32 v160, v168, v160
	v_add_f32_e32 v161, v169, v161
	v_permlane16_swap_b32_e32 v162, v166
	v_permlane16_swap_b32_e32 v163, v167
	v_permlane16_swap_b32_e32 v164, v160
	v_permlane16_swap_b32_e32 v165, v161
	v_pk_add_f32 v[162:163], v[162:163], v[166:167]
	v_pk_add_f32 v[160:161], v[164:165], v[160:161]
	v_ashrrev_i32_e32 v141, 31, v140
	v_cndmask_b32_e32 v156, v162, v160, vcc
	v_lshlrev_b64 v[168:169], 10, v[140:141]
	v_cndmask_b32_e32 v167, v161, v163, vcc
	v_mov_b32_dpp v164, v156 row_ror:8 row_mask:0xf bank_mask:0xf bound_ctrl:1
	v_cndmask_b32_e32 v156, v163, v161, vcc
	v_cndmask_b32_e32 v166, v160, v162, vcc
	v_or_b32_e32 v168, v168, v132
	v_mov_b32_dpp v165, v156 row_ror:8 row_mask:0xf bank_mask:0xf bound_ctrl:1
	v_pk_add_f32 v[160:161], v[166:167], v[164:165]
	v_lshl_add_u64 v[170:171], v[168:169], 2, s[70:71]
	v_pk_add_f32 v[160:161], v[134:135], v[160:161]
	global_store_dwordx2 v[170:171], v[160:161], off
	v_cvt_pk_bf16_f32 v156, v160, v161
	v_lshl_add_u64 v[162:163], v[168:169], 1, s[8:9]
	v_pk_mul_f32 v[160:161], v[160:161], v[160:161]
	global_store_dword v[162:163], v156, off
	v_add_f32_e32 v156, v160, v161
	s_nop 1
	v_add_f32_dpp v156, v156, v156 quad_perm:[1,0,3,2] row_mask:0xf bank_mask:0xf bound_ctrl:1
	s_nop 1
	v_add_f32_dpp v156, v156, v156 quad_perm:[2,3,0,1] row_mask:0xf bank_mask:0xf bound_ctrl:1
	s_nop 1
	v_add_f32_dpp v156, v156, v156 row_ror:4 row_mask:0xf bank_mask:0xf bound_ctrl:1
	s_nop 1
	v_add_f32_dpp v156, v156, v156 row_ror:8 row_mask:0xf bank_mask:0xf bound_ctrl:1
	v_mov_b32_e32 v159, v156
	s_nop 1
	v_permlane16_swap_b32_e32 v156, v159
	v_add_f32_e32 v156, v156, v159
	v_mov_b32_e32 v159, v156
	s_nop 1
	v_permlane32_swap_b32_e32 v156, v159
	s_and_saveexec_b64 s[16:17], s[0:1]
	s_cbranch_execz .LBB0_1249
	v_lshlrev_b64 v[160:161], 5, v[140:141]
	v_add_f32_e32 v156, v156, v159
	v_lshl_add_u64 v[160:161], s[14:15], 0, v[160:161]
	global_store_dword v[160:161], v156, off

.LBB0_1252:
	s_or_b64 exec, exec, s[18:19]
	v_add_u32_e32 v140, s23, v140
	v_min_i32_e32 v140, 0x3fff, v140
	v_ashrrev_i32_e32 v141, 31, v140
	v_lshlrev_b64 v[140:141], 9, v[140:141]
	v_lshl_or_b32 v140, v128, 2, v140
	v_lshl_add_u64 v[142:143], s[10:11], 0, v[140:141]
	v_or_b32_e32 v156, 0x100, v140
	v_mov_b32_e32 v157, v141
	v_lshl_add_u64 v[140:141], s[12:13], 0, v[140:141]
	v_lshl_add_u64 v[158:159], s[10:11], 0, v[156:157]
	v_lshl_add_u64 v[156:157], s[12:13], 0, v[156:157]
	global_load_dword v143, v[142:143], off
	s_nop 0
	global_load_dword v152, v[158:159], off
	s_nop 0
	global_load_dword v141, v[140:141], off
	s_nop 0
	global_load_dword v140, v[156:157], off
	ds_bpermute_b32 v142, v133, v153
	ds_bpermute_b32 v192, v144, v153
	ds_bpermute_b32 v194, v145, v153
	ds_bpermute_b32 v196, v146, v153
	ds_bpermute_b32 v198, v147, v153
	ds_bpermute_b32 v200, v148, v153
	ds_bpermute_b32 v202, v149, v153
	ds_bpermute_b32 v204, v150, v153
	ds_bpermute_b32 v206, v133, v151
	ds_bpermute_b32 v208, v144, v151
	ds_bpermute_b32 v210, v145, v151
	ds_bpermute_b32 v212, v146, v151
	ds_bpermute_b32 v214, v147, v151
	ds_bpermute_b32 v216, v148, v151
	ds_bpermute_b32 v218, v149, v151
	ds_bpermute_b32 v220, v150, v151
	v_cvt_pk_f32_fp8_e32 v[156:157], v48
	v_cvt_pk_f32_fp8_sdwa v[158:159], v48 src0_sel:WORD_1
	v_cvt_pk_f32_fp8_e32 v[160:161], v49
	v_cvt_pk_f32_fp8_sdwa v[162:163], v49 src0_sel:WORD_1
	v_cvt_pk_f32_fp8_e32 v[164:165], v50
	v_cvt_pk_f32_fp8_sdwa v[166:167], v50 src0_sel:WORD_1
	v_cvt_pk_f32_fp8_e32 v[168:169], v51
	v_cvt_pk_f32_fp8_sdwa v[170:171], v51 src0_sel:WORD_1
	v_cvt_pk_f32_fp8_e32 v[172:173], v52
	v_cvt_pk_f32_fp8_sdwa v[174:175], v52 src0_sel:WORD_1
	v_cvt_pk_f32_fp8_e32 v[176:177], v53
	v_cvt_pk_f32_fp8_sdwa v[178:179], v53 src0_sel:WORD_1
	s_waitcnt vmcnt(3) lgkmcnt(15)
	v_pk_fma_f32 v[156:157], v[156:157], v[142:143], 0 op_sel_hi:[1,0,0]
	v_pk_fma_f32 v[158:159], v[158:159], v[142:143], 0 op_sel_hi:[1,0,0]
	v_pk_fma_f32 v[160:161], v[160:161], v[142:143], 0 op_sel_hi:[1,0,0]
	v_pk_fma_f32 v[162:163], v[162:163], v[142:143], 0 op_sel_hi:[1,0,0]
	v_pk_fma_f32 v[164:165], v[164:165], v[142:143], 0 op_sel_hi:[1,0,0]
	v_pk_fma_f32 v[166:167], v[166:167], v[142:143], 0 op_sel_hi:[1,0,0]
	v_pk_fma_f32 v[168:169], v[168:169], v[142:143], 0 op_sel_hi:[1,0,0]
	v_pk_fma_f32 v[170:171], v[170:171], v[142:143], 0 op_sel_hi:[1,0,0]
	s_waitcnt lgkmcnt(14)
	v_pk_fma_f32 v[156:157], v[172:173], v[192:193], v[156:157] op_sel_hi:[1,0,1]
	v_pk_fma_f32 v[158:159], v[174:175], v[192:193], v[158:159] op_sel_hi:[1,0,1]
	v_pk_fma_f32 v[160:161], v[176:177], v[192:193], v[160:161] op_sel_hi:[1,0,1]
	v_pk_fma_f32 v[162:163], v[178:179], v[192:193], v[162:163] op_sel_hi:[1,0,1]
	v_cvt_pk_f32_fp8_e32 v[172:173], v54
	v_cvt_pk_f32_fp8_sdwa v[174:175], v54 src0_sel:WORD_1
	v_cvt_pk_f32_fp8_e32 v[176:177], v55
	v_cvt_pk_f32_fp8_sdwa v[178:179], v55 src0_sel:WORD_1
	v_pk_fma_f32 v[164:165], v[172:173], v[192:193], v[164:165] op_sel_hi:[1,0,1]
	v_pk_fma_f32 v[166:167], v[174:175], v[192:193], v[166:167] op_sel_hi:[1,0,1]
	v_pk_fma_f32 v[168:169], v[176:177], v[192:193], v[168:169] op_sel_hi:[1,0,1]
	v_pk_fma_f32 v[170:171], v[178:179], v[192:193], v[170:171] op_sel_hi:[1,0,1]
	v_cvt_pk_f32_fp8_e32 v[172:173], v72
	v_cvt_pk_f32_fp8_sdwa v[174:175], v72 src0_sel:WORD_1
	v_cvt_pk_f32_fp8_e32 v[176:177], v73
	v_cvt_pk_f32_fp8_sdwa v[178:179], v73 src0_sel:WORD_1
	s_waitcnt lgkmcnt(13)
	v_pk_fma_f32 v[156:157], v[172:173], v[194:195], v[156:157] op_sel_hi:[1,0,1]
	v_pk_fma_f32 v[158:159], v[174:175], v[194:195], v[158:159] op_sel_hi:[1,0,1]
	v_pk_fma_f32 v[160:161], v[176:177], v[194:195], v[160:161] op_sel_hi:[1,0,1]
	v_pk_fma_f32 v[162:163], v[178:179], v[194:195], v[162:163] op_sel_hi:[1,0,1]
	v_cvt_pk_f32_fp8_e32 v[172:173], v74
	v_cvt_pk_f32_fp8_sdwa v[174:175], v74 src0_sel:WORD_1
	v_cvt_pk_f32_fp8_e32 v[176:177], v75
	v_cvt_pk_f32_fp8_sdwa v[178:179], v75 src0_sel:WORD_1
	v_pk_fma_f32 v[164:165], v[172:173], v[194:195], v[164:165] op_sel_hi:[1,0,1]
	v_pk_fma_f32 v[166:167], v[174:175], v[194:195], v[166:167] op_sel_hi:[1,0,1]
	v_pk_fma_f32 v[168:169], v[176:177], v[194:195], v[168:169] op_sel_hi:[1,0,1]
	v_pk_fma_f32 v[170:171], v[178:179], v[194:195], v[170:171] op_sel_hi:[1,0,1]
	v_cvt_pk_f32_fp8_e32 v[172:173], v76
	v_cvt_pk_f32_fp8_sdwa v[174:175], v76 src0_sel:WORD_1
	v_cvt_pk_f32_fp8_e32 v[176:177], v77
	v_cvt_pk_f32_fp8_sdwa v[178:179], v77 src0_sel:WORD_1
	s_waitcnt lgkmcnt(12)
	v_pk_fma_f32 v[156:157], v[172:173], v[196:197], v[156:157] op_sel_hi:[1,0,1]
	v_pk_fma_f32 v[158:159], v[174:175], v[196:197], v[158:159] op_sel_hi:[1,0,1]
	v_pk_fma_f32 v[160:161], v[176:177], v[196:197], v[160:161] op_sel_hi:[1,0,1]
	v_pk_fma_f32 v[162:163], v[178:179], v[196:197], v[162:163] op_sel_hi:[1,0,1]
	v_cvt_pk_f32_fp8_e32 v[172:173], v78
	v_cvt_pk_f32_fp8_sdwa v[174:175], v78 src0_sel:WORD_1
	v_cvt_pk_f32_fp8_e32 v[176:177], v79
	v_cvt_pk_f32_fp8_sdwa v[178:179], v79 src0_sel:WORD_1
	v_pk_fma_f32 v[164:165], v[172:173], v[196:197], v[164:165] op_sel_hi:[1,0,1]
	v_pk_fma_f32 v[166:167], v[174:175], v[196:197], v[166:167] op_sel_hi:[1,0,1]
	v_pk_fma_f32 v[168:169], v[176:177], v[196:197], v[168:169] op_sel_hi:[1,0,1]
	v_pk_fma_f32 v[170:171], v[178:179], v[196:197], v[170:171] op_sel_hi:[1,0,1]
	v_cvt_pk_f32_fp8_e32 v[172:173], v80
	v_cvt_pk_f32_fp8_sdwa v[174:175], v80 src0_sel:WORD_1
	v_cvt_pk_f32_fp8_e32 v[176:177], v81
	v_cvt_pk_f32_fp8_sdwa v[178:179], v81 src0_sel:WORD_1
	s_waitcnt lgkmcnt(11)
	v_pk_fma_f32 v[156:157], v[172:173], v[198:199], v[156:157] op_sel_hi:[1,0,1]
	v_pk_fma_f32 v[158:159], v[174:175], v[198:199], v[158:159] op_sel_hi:[1,0,1]
	v_pk_fma_f32 v[160:161], v[176:177], v[198:199], v[160:161] op_sel_hi:[1,0,1]
	v_pk_fma_f32 v[162:163], v[178:179], v[198:199], v[162:163] op_sel_hi:[1,0,1]
	v_cvt_pk_f32_fp8_e32 v[172:173], v82
	v_cvt_pk_f32_fp8_sdwa v[174:175], v82 src0_sel:WORD_1
	v_cvt_pk_f32_fp8_e32 v[176:177], v83
	v_cvt_pk_f32_fp8_sdwa v[178:179], v83 src0_sel:WORD_1
	v_pk_fma_f32 v[164:165], v[172:173], v[198:199], v[164:165] op_sel_hi:[1,0,1]
	v_pk_fma_f32 v[166:167], v[174:175], v[198:199], v[166:167] op_sel_hi:[1,0,1]
	v_pk_fma_f32 v[168:169], v[176:177], v[198:199], v[168:169] op_sel_hi:[1,0,1]
	v_pk_fma_f32 v[170:171], v[178:179], v[198:199], v[170:171] op_sel_hi:[1,0,1]
	v_cvt_pk_f32_fp8_e32 v[172:173], v84
	v_cvt_pk_f32_fp8_sdwa v[174:175], v84 src0_sel:WORD_1
	v_cvt_pk_f32_fp8_e32 v[176:177], v85
	v_cvt_pk_f32_fp8_sdwa v[178:179], v85 src0_sel:WORD_1
	s_waitcnt lgkmcnt(10)
	v_pk_fma_f32 v[156:157], v[172:173], v[200:201], v[156:157] op_sel_hi:[1,0,1]
	v_pk_fma_f32 v[158:159], v[174:175], v[200:201], v[158:159] op_sel_hi:[1,0,1]
	v_pk_fma_f32 v[160:161], v[176:177], v[200:201], v[160:161] op_sel_hi:[1,0,1]
	v_pk_fma_f32 v[162:163], v[178:179], v[200:201], v[162:163] op_sel_hi:[1,0,1]
	v_cvt_pk_f32_fp8_e32 v[172:173], v86
	v_cvt_pk_f32_fp8_sdwa v[174:175], v86 src0_sel:WORD_1
	v_cvt_pk_f32_fp8_e32 v[176:177], v87
	v_cvt_pk_f32_fp8_sdwa v[178:179], v87 src0_sel:WORD_1
	v_pk_fma_f32 v[164:165], v[172:173], v[200:201], v[164:165] op_sel_hi:[1,0,1]
	v_pk_fma_f32 v[166:167], v[174:175], v[200:201], v[166:167] op_sel_hi:[1,0,1]
	v_pk_fma_f32 v[168:169], v[176:177], v[200:201], v[168:169] op_sel_hi:[1,0,1]
	v_pk_fma_f32 v[170:171], v[178:179], v[200:201], v[170:171] op_sel_hi:[1,0,1]
	v_cvt_pk_f32_fp8_e32 v[172:173], v88
	v_cvt_pk_f32_fp8_sdwa v[174:175], v88 src0_sel:WORD_1
	v_cvt_pk_f32_fp8_e32 v[176:177], v89
	v_cvt_pk_f32_fp8_sdwa v[178:179], v89 src0_sel:WORD_1
	s_waitcnt lgkmcnt(9)
	v_pk_fma_f32 v[156:157], v[172:173], v[202:203], v[156:157] op_sel_hi:[1,0,1]
	v_pk_fma_f32 v[158:159], v[174:175], v[202:203], v[158:159] op_sel_hi:[1,0,1]
	v_pk_fma_f32 v[160:161], v[176:177], v[202:203], v[160:161] op_sel_hi:[1,0,1]
	v_pk_fma_f32 v[162:163], v[178:179], v[202:203], v[162:163] op_sel_hi:[1,0,1]
	v_cvt_pk_f32_fp8_e32 v[172:173], v90
	v_cvt_pk_f32_fp8_sdwa v[174:175], v90 src0_sel:WORD_1
	v_cvt_pk_f32_fp8_e32 v[176:177], v91
	v_cvt_pk_f32_fp8_sdwa v[178:179], v91 src0_sel:WORD_1
	v_pk_fma_f32 v[164:165], v[172:173], v[202:203], v[164:165] op_sel_hi:[1,0,1]
	v_pk_fma_f32 v[166:167], v[174:175], v[202:203], v[166:167] op_sel_hi:[1,0,1]
	v_pk_fma_f32 v[168:169], v[176:177], v[202:203], v[168:169] op_sel_hi:[1,0,1]
	v_pk_fma_f32 v[170:171], v[178:179], v[202:203], v[170:171] op_sel_hi:[1,0,1]
	v_cvt_pk_f32_fp8_e32 v[172:173], v92
	v_cvt_pk_f32_fp8_sdwa v[174:175], v92 src0_sel:WORD_1
	v_cvt_pk_f32_fp8_e32 v[176:177], v93
	v_cvt_pk_f32_fp8_sdwa v[178:179], v93 src0_sel:WORD_1
	s_waitcnt lgkmcnt(8)
	v_pk_fma_f32 v[156:157], v[172:173], v[204:205], v[156:157] op_sel_hi:[1,0,1]
	v_pk_fma_f32 v[158:159], v[174:175], v[204:205], v[158:159] op_sel_hi:[1,0,1]
	v_pk_fma_f32 v[160:161], v[176:177], v[204:205], v[160:161] op_sel_hi:[1,0,1]
	v_pk_fma_f32 v[162:163], v[178:179], v[204:205], v[162:163] op_sel_hi:[1,0,1]
	v_cvt_pk_f32_fp8_e32 v[172:173], v94
	v_cvt_pk_f32_fp8_sdwa v[174:175], v94 src0_sel:WORD_1
	v_cvt_pk_f32_fp8_e32 v[176:177], v95
	v_cvt_pk_f32_fp8_sdwa v[178:179], v95 src0_sel:WORD_1
	v_pk_fma_f32 v[164:165], v[172:173], v[204:205], v[164:165] op_sel_hi:[1,0,1]
	v_pk_fma_f32 v[166:167], v[174:175], v[204:205], v[166:167] op_sel_hi:[1,0,1]
	v_pk_fma_f32 v[168:169], v[176:177], v[204:205], v[168:169] op_sel_hi:[1,0,1]
	v_pk_fma_f32 v[170:171], v[178:179], v[204:205], v[170:171] op_sel_hi:[1,0,1]
	v_cvt_pk_f32_fp8_e32 v[172:173], v96
	v_cvt_pk_f32_fp8_sdwa v[174:175], v96 src0_sel:WORD_1
	v_cvt_pk_f32_fp8_e32 v[176:177], v97
	v_cvt_pk_f32_fp8_sdwa v[178:179], v97 src0_sel:WORD_1
	s_waitcnt lgkmcnt(7)
	v_pk_fma_f32 v[156:157], v[172:173], v[206:207], v[156:157] op_sel_hi:[1,0,1]
	v_pk_fma_f32 v[158:159], v[174:175], v[206:207], v[158:159] op_sel_hi:[1,0,1]
	v_pk_fma_f32 v[160:161], v[176:177], v[206:207], v[160:161] op_sel_hi:[1,0,1]
	v_pk_fma_f32 v[162:163], v[178:179], v[206:207], v[162:163] op_sel_hi:[1,0,1]
	v_cvt_pk_f32_fp8_e32 v[172:173], v98
	v_cvt_pk_f32_fp8_sdwa v[174:175], v98 src0_sel:WORD_1
	v_cvt_pk_f32_fp8_e32 v[176:177], v99
	v_cvt_pk_f32_fp8_sdwa v[178:179], v99 src0_sel:WORD_1
	v_pk_fma_f32 v[164:165], v[172:173], v[206:207], v[164:165] op_sel_hi:[1,0,1]
	v_pk_fma_f32 v[166:167], v[174:175], v[206:207], v[166:167] op_sel_hi:[1,0,1]
	v_pk_fma_f32 v[168:169], v[176:177], v[206:207], v[168:169] op_sel_hi:[1,0,1]
	v_pk_fma_f32 v[170:171], v[178:179], v[206:207], v[170:171] op_sel_hi:[1,0,1]
	v_cvt_pk_f32_fp8_e32 v[172:173], v100
	v_cvt_pk_f32_fp8_sdwa v[174:175], v100 src0_sel:WORD_1
	v_cvt_pk_f32_fp8_e32 v[176:177], v101
	v_cvt_pk_f32_fp8_sdwa v[178:179], v101 src0_sel:WORD_1
	s_waitcnt lgkmcnt(6)
	v_pk_fma_f32 v[156:157], v[172:173], v[208:209], v[156:157] op_sel_hi:[1,0,1]
	v_pk_fma_f32 v[158:159], v[174:175], v[208:209], v[158:159] op_sel_hi:[1,0,1]
	v_pk_fma_f32 v[160:161], v[176:177], v[208:209], v[160:161] op_sel_hi:[1,0,1]
	v_pk_fma_f32 v[162:163], v[178:179], v[208:209], v[162:163] op_sel_hi:[1,0,1]
	v_cvt_pk_f32_fp8_e32 v[172:173], v102
	v_cvt_pk_f32_fp8_sdwa v[174:175], v102 src0_sel:WORD_1
	v_cvt_pk_f32_fp8_e32 v[176:177], v103
	v_cvt_pk_f32_fp8_sdwa v[178:179], v103 src0_sel:WORD_1
	v_pk_fma_f32 v[164:165], v[172:173], v[208:209], v[164:165] op_sel_hi:[1,0,1]
	v_pk_fma_f32 v[166:167], v[174:175], v[208:209], v[166:167] op_sel_hi:[1,0,1]
	v_pk_fma_f32 v[168:169], v[176:177], v[208:209], v[168:169] op_sel_hi:[1,0,1]
	v_pk_fma_f32 v[170:171], v[178:179], v[208:209], v[170:171] op_sel_hi:[1,0,1]
	v_cvt_pk_f32_fp8_e32 v[172:173], v104
	v_cvt_pk_f32_fp8_sdwa v[174:175], v104 src0_sel:WORD_1
	v_cvt_pk_f32_fp8_e32 v[176:177], v105
	v_cvt_pk_f32_fp8_sdwa v[178:179], v105 src0_sel:WORD_1
	s_waitcnt lgkmcnt(5)
	v_pk_fma_f32 v[156:157], v[172:173], v[210:211], v[156:157] op_sel_hi:[1,0,1]
	v_pk_fma_f32 v[158:159], v[174:175], v[210:211], v[158:159] op_sel_hi:[1,0,1]
	v_pk_fma_f32 v[160:161], v[176:177], v[210:211], v[160:161] op_sel_hi:[1,0,1]
	v_pk_fma_f32 v[162:163], v[178:179], v[210:211], v[162:163] op_sel_hi:[1,0,1]
	v_cvt_pk_f32_fp8_e32 v[172:173], v106
	v_cvt_pk_f32_fp8_sdwa v[174:175], v106 src0_sel:WORD_1
	v_cvt_pk_f32_fp8_e32 v[176:177], v107
	v_cvt_pk_f32_fp8_sdwa v[178:179], v107 src0_sel:WORD_1
	v_pk_fma_f32 v[164:165], v[172:173], v[210:211], v[164:165] op_sel_hi:[1,0,1]
	v_pk_fma_f32 v[166:167], v[174:175], v[210:211], v[166:167] op_sel_hi:[1,0,1]
	v_pk_fma_f32 v[168:169], v[176:177], v[210:211], v[168:169] op_sel_hi:[1,0,1]
	v_pk_fma_f32 v[170:171], v[178:179], v[210:211], v[170:171] op_sel_hi:[1,0,1]
	v_cvt_pk_f32_fp8_e32 v[172:173], v108
	v_cvt_pk_f32_fp8_sdwa v[174:175], v108 src0_sel:WORD_1
	v_cvt_pk_f32_fp8_e32 v[176:177], v109
	v_cvt_pk_f32_fp8_sdwa v[178:179], v109 src0_sel:WORD_1
	s_waitcnt lgkmcnt(4)
	v_pk_fma_f32 v[156:157], v[172:173], v[212:213], v[156:157] op_sel_hi:[1,0,1]
	v_pk_fma_f32 v[158:159], v[174:175], v[212:213], v[158:159] op_sel_hi:[1,0,1]
	v_pk_fma_f32 v[160:161], v[176:177], v[212:213], v[160:161] op_sel_hi:[1,0,1]
	v_pk_fma_f32 v[162:163], v[178:179], v[212:213], v[162:163] op_sel_hi:[1,0,1]
	v_cvt_pk_f32_fp8_e32 v[172:173], v110
	v_cvt_pk_f32_fp8_sdwa v[174:175], v110 src0_sel:WORD_1
	v_cvt_pk_f32_fp8_e32 v[176:177], v111
	v_cvt_pk_f32_fp8_sdwa v[178:179], v111 src0_sel:WORD_1
	v_pk_fma_f32 v[164:165], v[172:173], v[212:213], v[164:165] op_sel_hi:[1,0,1]
	v_pk_fma_f32 v[166:167], v[174:175], v[212:213], v[166:167] op_sel_hi:[1,0,1]
	v_pk_fma_f32 v[168:169], v[176:177], v[212:213], v[168:169] op_sel_hi:[1,0,1]
	v_pk_fma_f32 v[170:171], v[178:179], v[212:213], v[170:171] op_sel_hi:[1,0,1]
	v_cvt_pk_f32_fp8_e32 v[172:173], v112
	v_cvt_pk_f32_fp8_sdwa v[174:175], v112 src0_sel:WORD_1
	v_cvt_pk_f32_fp8_e32 v[176:177], v113
	v_cvt_pk_f32_fp8_sdwa v[178:179], v113 src0_sel:WORD_1
	s_waitcnt lgkmcnt(3)
	v_pk_fma_f32 v[156:157], v[172:173], v[214:215], v[156:157] op_sel_hi:[1,0,1]
	v_pk_fma_f32 v[158:159], v[174:175], v[214:215], v[158:159] op_sel_hi:[1,0,1]
	v_pk_fma_f32 v[160:161], v[176:177], v[214:215], v[160:161] op_sel_hi:[1,0,1]
	v_pk_fma_f32 v[162:163], v[178:179], v[214:215], v[162:163] op_sel_hi:[1,0,1]
	v_cvt_pk_f32_fp8_e32 v[172:173], v114
	v_cvt_pk_f32_fp8_sdwa v[174:175], v114 src0_sel:WORD_1
	v_cvt_pk_f32_fp8_e32 v[176:177], v115
	v_cvt_pk_f32_fp8_sdwa v[178:179], v115 src0_sel:WORD_1
	v_pk_fma_f32 v[164:165], v[172:173], v[214:215], v[164:165] op_sel_hi:[1,0,1]
	v_pk_fma_f32 v[166:167], v[174:175], v[214:215], v[166:167] op_sel_hi:[1,0,1]
	v_pk_fma_f32 v[168:169], v[176:177], v[214:215], v[168:169] op_sel_hi:[1,0,1]
	v_pk_fma_f32 v[170:171], v[178:179], v[214:215], v[170:171] op_sel_hi:[1,0,1]
	v_cvt_pk_f32_fp8_e32 v[172:173], v116
	v_cvt_pk_f32_fp8_sdwa v[174:175], v116 src0_sel:WORD_1
	v_cvt_pk_f32_fp8_e32 v[176:177], v117
	v_cvt_pk_f32_fp8_sdwa v[178:179], v117 src0_sel:WORD_1
	s_waitcnt lgkmcnt(2)
	v_pk_fma_f32 v[156:157], v[172:173], v[216:217], v[156:157] op_sel_hi:[1,0,1]
	v_pk_fma_f32 v[158:159], v[174:175], v[216:217], v[158:159] op_sel_hi:[1,0,1]
	v_pk_fma_f32 v[160:161], v[176:177], v[216:217], v[160:161] op_sel_hi:[1,0,1]
	v_pk_fma_f32 v[162:163], v[178:179], v[216:217], v[162:163] op_sel_hi:[1,0,1]
	v_cvt_pk_f32_fp8_e32 v[172:173], v118
	v_cvt_pk_f32_fp8_sdwa v[174:175], v118 src0_sel:WORD_1
	v_cvt_pk_f32_fp8_e32 v[176:177], v119
	v_cvt_pk_f32_fp8_sdwa v[178:179], v119 src0_sel:WORD_1
	v_pk_fma_f32 v[164:165], v[172:173], v[216:217], v[164:165] op_sel_hi:[1,0,1]
	v_pk_fma_f32 v[166:167], v[174:175], v[216:217], v[166:167] op_sel_hi:[1,0,1]
	v_pk_fma_f32 v[168:169], v[176:177], v[216:217], v[168:169] op_sel_hi:[1,0,1]
	v_pk_fma_f32 v[170:171], v[178:179], v[216:217], v[170:171] op_sel_hi:[1,0,1]
	v_cvt_pk_f32_fp8_e32 v[172:173], v120
	v_cvt_pk_f32_fp8_sdwa v[174:175], v120 src0_sel:WORD_1
	v_cvt_pk_f32_fp8_e32 v[176:177], v121
	v_cvt_pk_f32_fp8_sdwa v[178:179], v121 src0_sel:WORD_1
	s_waitcnt lgkmcnt(1)
	v_pk_fma_f32 v[156:157], v[172:173], v[218:219], v[156:157] op_sel_hi:[1,0,1]
	v_pk_fma_f32 v[158:159], v[174:175], v[218:219], v[158:159] op_sel_hi:[1,0,1]
	v_pk_fma_f32 v[160:161], v[176:177], v[218:219], v[160:161] op_sel_hi:[1,0,1]
	v_pk_fma_f32 v[162:163], v[178:179], v[218:219], v[162:163] op_sel_hi:[1,0,1]
	v_cvt_pk_f32_fp8_e32 v[172:173], v122
	v_cvt_pk_f32_fp8_sdwa v[174:175], v122 src0_sel:WORD_1
	v_cvt_pk_f32_fp8_e32 v[176:177], v123
	v_cvt_pk_f32_fp8_sdwa v[178:179], v123 src0_sel:WORD_1
	v_pk_fma_f32 v[164:165], v[172:173], v[218:219], v[164:165] op_sel_hi:[1,0,1]
	v_pk_fma_f32 v[166:167], v[174:175], v[218:219], v[166:167] op_sel_hi:[1,0,1]
	v_pk_fma_f32 v[168:169], v[176:177], v[218:219], v[168:169] op_sel_hi:[1,0,1]
	v_pk_fma_f32 v[170:171], v[178:179], v[218:219], v[170:171] op_sel_hi:[1,0,1]
	v_cvt_pk_f32_fp8_e32 v[172:173], v124
	v_cvt_pk_f32_fp8_sdwa v[174:175], v124 src0_sel:WORD_1
	v_cvt_pk_f32_fp8_e32 v[176:177], v125
	v_cvt_pk_f32_fp8_sdwa v[178:179], v125 src0_sel:WORD_1
	s_waitcnt lgkmcnt(0)
	v_pk_fma_f32 v[156:157], v[172:173], v[220:221], v[156:157] op_sel_hi:[1,0,1]
	v_pk_fma_f32 v[158:159], v[174:175], v[220:221], v[158:159] op_sel_hi:[1,0,1]
	v_pk_fma_f32 v[160:161], v[176:177], v[220:221], v[160:161] op_sel_hi:[1,0,1]
	v_pk_fma_f32 v[162:163], v[178:179], v[220:221], v[162:163] op_sel_hi:[1,0,1]
	v_cvt_pk_f32_fp8_e32 v[172:173], v126
	v_cvt_pk_f32_fp8_sdwa v[174:175], v126 src0_sel:WORD_1
	v_cvt_pk_f32_fp8_e32 v[176:177], v127
	v_cvt_pk_f32_fp8_sdwa v[178:179], v127 src0_sel:WORD_1
	v_pk_fma_f32 v[164:165], v[172:173], v[220:221], v[164:165] op_sel_hi:[1,0,1]
	v_pk_fma_f32 v[166:167], v[174:175], v[220:221], v[166:167] op_sel_hi:[1,0,1]
	v_pk_fma_f32 v[168:169], v[176:177], v[220:221], v[168:169] op_sel_hi:[1,0,1]
	v_pk_fma_f32 v[170:171], v[178:179], v[220:221], v[170:171] op_sel_hi:[1,0,1]
	v_permlane32_swap_b32_e32 v156, v164
	v_permlane32_swap_b32_e32 v157, v165
	v_permlane32_swap_b32_e32 v158, v166
	v_permlane32_swap_b32_e32 v159, v167
	v_permlane32_swap_b32_e32 v160, v168
	v_permlane32_swap_b32_e32 v161, v169
	v_permlane32_swap_b32_e32 v162, v170
	v_permlane32_swap_b32_e32 v163, v171
	v_add_f32_e32 v156, v156, v164
	v_add_f32_e32 v157, v157, v165
	v_add_f32_e32 v158, v158, v166
	v_add_f32_e32 v159, v159, v167
	v_add_f32_e32 v160, v160, v168
	v_add_f32_e32 v161, v161, v169
	v_add_f32_e32 v162, v162, v170
	v_add_f32_e32 v163, v163, v171
	v_permlane16_swap_b32_e32 v156, v160
	v_permlane16_swap_b32_e32 v157, v161
	v_permlane16_swap_b32_e32 v158, v162
	v_permlane16_swap_b32_e32 v159, v163
	v_pk_add_f32 v[156:157], v[156:157], v[160:161]
	v_pk_add_f32 v[158:159], v[158:159], v[162:163]
	v_lshlrev_b64 v[164:165], 10, v[138:139]
	v_cndmask_b32_e32 v142, v156, v158, vcc
	v_cndmask_b32_e32 v163, v159, v157, vcc
	v_cndmask_b32_e32 v162, v158, v156, vcc
	v_mov_b32_dpp v160, v142 row_ror:8 row_mask:0xf bank_mask:0xf bound_ctrl:1
	v_cndmask_b32_e32 v142, v157, v159, vcc
	v_or_b32_e32 v164, v164, v132
	v_lshl_add_u64 v[166:167], v[164:165], 2, s[70:71]
	v_mov_b32_dpp v161, v142 row_ror:8 row_mask:0xf bank_mask:0xf bound_ctrl:1
	v_pk_add_f32 v[156:157], v[162:163], v[160:161]
	v_lshl_add_u64 v[158:159], v[164:165], 1, s[8:9]
	v_pk_add_f32 v[156:157], v[136:137], v[156:157]
	global_store_dwordx2 v[166:167], v[156:157], off
	v_cvt_pk_bf16_f32 v142, v156, v157
	v_pk_mul_f32 v[156:157], v[156:157], v[156:157]
	global_store_dword v[158:159], v142, off
	v_add_f32_e32 v142, v156, v157
	s_nop 1
	v_add_f32_dpp v142, v142, v142 quad_perm:[1,0,3,2] row_mask:0xf bank_mask:0xf bound_ctrl:1
	s_nop 1
	v_add_f32_dpp v142, v142, v142 quad_perm:[2,3,0,1] row_mask:0xf bank_mask:0xf bound_ctrl:1
	s_nop 1
	v_add_f32_dpp v142, v142, v142 row_ror:4 row_mask:0xf bank_mask:0xf bound_ctrl:1
	s_nop 1
	v_add_f32_dpp v142, v142, v142 row_ror:8 row_mask:0xf bank_mask:0xf bound_ctrl:1
	v_mov_b32_e32 v151, v142
	s_nop 1
	v_permlane16_swap_b32_e32 v142, v151
	v_add_f32_e32 v142, v142, v151
	v_mov_b32_e32 v151, v142
	s_nop 1
	v_permlane32_swap_b32_e32 v142, v151
	s_and_saveexec_b64 s[2:3], s[0:1]
	s_cbranch_execz .LBB0_1243
	v_lshlrev_b64 v[156:157], 5, v[138:139]
	v_add_f32_e32 v142, v142, v151
	v_lshl_add_u64 v[156:157], s[14:15], 0, v[156:157]
	global_store_dword v[156:157], v142, off
	s_branch .LBB0_1243
